# SP2 GEMM phases: first K-iteration after an epilogue uses relaxed vmcnt so the epilogue's store drain overlaps the first two super-phases
# speedup vs baseline: 1.0113x; 1.0113x over previous
; #define LAS __attribute__((address_space(3)))
; __global__ void __launch_bounds__(512, 2) mk_fwd(Args a) {
;     extern __shared__ __attribute__((aligned(16))) unsigned char lds_raw[];
;     LAS unsigned char* lds = (LAS unsigned char*)lds_raw;
;     cg::grid_group grid = cg::this_grid();
;     const int tid = threadIdx.x, lane = tid & 63, wave = __builtin_amdgcn_readfirstlane(tid >> 6);
;     const int G = gridDim.x, bx = blockIdx.x;
;     const float* x_p = a.in[0]; const float* x_s = a.in[1]; const float* rel_bias = a.in[2]; const float* g_mix = a.in[3]; const float* w_in = a.in[4]; const float* b_gate = a.in[5];
;     const float* w_a = a.in[6]; const float* w_b = a.in[7]; const float* w_out = a.in[8]; const float* sink = a.in[9]; const float* g_mlp = a.in[10]; const float* w_up = a.in[11]; const float* w_dn = a.in[12]; const float* g_fin = a.in[13];
;     unsigned char* ws = a.ws; float* out = a.out;
;     bf16* Win_t = (bf16*)(ws + WS_WIN); bf16* Wa_t = (bf16*)(ws + WS_WA); bf16* Wb_t = (bf16*)(ws + WS_WB); bf16* Wout_t = (bf16*)(ws + WS_WOUT); bf16* Wup_t = (bf16*)(ws + WS_WUP); bf16* Wdn_t = (bf16*)(ws + WS_WDN);
;     float* SSQ1 = (float*)(ws + WS_SSQ1); float* SSQ2 = (float*)(ws + WS_SSQ2);
;     bf16* XN = (bf16*)(ws + WS_XN); bf16* OA = (bf16*)(ws + WS_OA); bf16* OB = (bf16*)(ws + WS_OB); bf16* X1B = (bf16*)(ws + WS_X1B);
;     bf16* Zb = (bf16*)(ws + WS_Z); bf16* MRG = (bf16*)(ws + WS_MRG); bf16* Hb = (bf16*)(ws + WS_H); bf16* Gt = (bf16*)(ws + WS_G);
;     bf16* OBG = (bf16*)((unsigned char*)out + DO_OBG); float* LSE = (float*)((unsigned char*)out + DO_LSE);
;     grid.sync();
;     const int gw = bx * 8 + wave, NGW = G * 8;
;     unsigned* bar_ctr = (unsigned*)ws; unsigned bar_n = 0;
;     const unsigned my_xcc = (unsigned)__builtin_amdgcn_s_getreg((3 << 11) | 20) & 0xFu;
;     if (tid == 0) *(LAS unsigned*)(lds + RING_BYTES + 64) = __hip_atomic_fetch_add(bar_ctr + 512 + 64 * (my_xcc & 7u), 1u, __ATOMIC_RELAXED, __HIP_MEMORY_SCOPE_AGENT);
_Z6mk_fwd4Args:
	s_load_dword s24, s[0:1], 0x80
	s_load_dwordx16 s[36:51], s[0:1], 0x0
	s_load_dwordx16 s[8:23], s[0:1], 0x40
	v_and_b32_e32 v254, 0x3ff, v0
	s_nop 0
	v_readfirstlane_b32 s25, v254
	s_waitcnt lgkmcnt(0)
	s_mov_b32 s100, 0
	s_mov_b32 s99, 0
	s_getreg_b32 s3, hwreg(HW_REG_XCC_ID, 0, 4)
	v_cmp_eq_u32_e64 s[0:1], 0, v254
	s_mov_b64 s[4:5], exec
	s_nop 0
	v_writelane_b32 v255, s0, 0
	s_nop 1
	v_writelane_b32 v255, s1, 1
	s_and_b64 s[0:1], s[4:5], s[0:1]
	s_mov_b64 exec, s[0:1]
	s_cbranch_execz .LBB0_14
	s_mov_b64 s[26:27], exec
	v_mbcnt_lo_u32_b32 v0, s26, 0
	v_mbcnt_hi_u32_b32 v0, s27, v0
	v_cmp_eq_u32_e32 vcc, 0, v0
	s_and_saveexec_b64 s[6:7], vcc
	s_cbranch_execz .LBB0_13
	s_lshl_b32 s0, s3, 8
	s_and_b32 s0, s0, 0x700
	s_bcnt1_i32_b64 s1, s[26:27]
	v_mov_b32_e32 v1, s0
	v_mov_b32_e32 v2, s1
	global_atomic_add v1, v1, v2, s[22:23] offset:2048 sc0

; template <class Epi, class Sched, bool ALIGN_EPI = false, bool SP2 = false, bool FP8 = false>
; __device__ __forceinline__ void gemm_phase(PG8_LAS unsigned char* lds, const Gemm g, const Sched& S, const Epi& E) {
;     ...
;     for (;;) {
;         const bool has_next = S.next(ui + 1, nxt);
;         const char* nA = has_next ? (const char*)g.A + (size_t)nxt.pm * tstep : cA; const char* nB = has_next ? (const char*)g.Bt + (size_t)nxt.pn * tstep : cB;
; #pragma unroll 1
;         for (int t = 0; t < nt; t += 2) {
.LBB0_296:
	s_mov_b32 s99, 1
	s_mov_b64 s[2:3], 0

; #define PG8_STAGE(bufoff, gbase, voff) do { _Pragma("unroll") for (int _i = 0; _i < 2; ++_i) { unsigned vo_ = (voff)[_i]; if constexpr (FP8) asm volatile("" : "+v"(vo_)); \
;         __builtin_amdgcn_global_load_lds((const unsigned*)((const char*)(gbase) + vo_), (PG8_LAS unsigned*)(lds + (bufoff) + ldsw + _i * 8192), 16, 0, 0); } } while (0)
; #define PG8_LDA(dst, b, h) do { _Pragma("unroll") for (int m = 0; m < 4; ++m) _Pragma("unroll") for (int k = 0; k < 2; ++k) dst[m][k] = *(const PG8_LAS bf16x8*)(lds + PG8_SA(b, h) + aoff + m * 2048 + k * 1024); } while (0)
; #define PG8_LDB(dst, b, h) do { _Pragma("unroll") for (int n = 0; n < 2; ++n) _Pragma("unroll") for (int k = 0; k < 2; ++k) dst[n][k] = *(const PG8_LAS bf16x8*)(lds + PG8_SB(b, h) + boff + n * 2048 + k * 1024); } while (0)
; #define PG8_WAIT_V(n) asm volatile("s_waitcnt vmcnt(" #n ")" ::: "memory")
; #define PG8_WAIT_L(n) asm volatile("s_waitcnt lgkmcnt(" #n ")" ::: "memory")
; #define PG8_BAR __builtin_amdgcn_s_barrier()
; #define PG8_SCHED __builtin_amdgcn_sched_barrier(0)
; template <class Epi, class Sched, bool ALIGN_EPI = false, bool SP2 = false, bool FP8 = false>
; __device__ __forceinline__ void gemm_phase(PG8_LAS unsigned char* lds, const Gemm g, const Sched& S, const Epi& E) {
;     ...
;             PG8_LDB(B0, 0, 0); PG8_LDB(B1, 0, 1); PG8_SCHED; PG8_LDA(At, 0, 0); PG8_STAGE(PG8_SA(1, 1), a1 + hstep, voffA);
;             PG8_WAIT_V(8); PG8_WAIT_L(0); PG8_BAR; PG8_MMA(0, 0, At, B0); PG8_MMA(0, 1, At, B1); PG8_BAR; PG8_SCHED;
;             PG8_LDA(At, 0, 1); PG8_STAGE(PG8_SB(0, 0), b2, voffB); PG8_STAGE(PG8_SB(0, 1), b2 + hstep, voffB); PG8_STAGE(PG8_SA(0, 0), a2, voffA);
;             PG8_WAIT_V(8); PG8_WAIT_L(0); PG8_BAR; PG8_MMA(1, 0, At, B0); PG8_MMA(1, 1, At, B1); PG8_BAR; PG8_SCHED;
.LBB0_305:
	s_add_u32 s52, s10, 0xfffe8080
	s_addc_u32 s53, s11, -1
	s_and_b64 s[0:1], s[62:63], exec
	s_cselect_b32 s65, s5, s53
	s_cselect_b32 s64, s4, s52
	s_add_i32 s52, 0, 0x10000
	v_add_u32_e32 v128, s52, v152
	ds_read_b128 v[134:137], v128
	ds_read_b128 v[138:141], v128 offset:1024
	ds_read_b128 v[156:159], v128 offset:2048
	ds_read_b128 v[160:163], v128 offset:3072
	v_add_u32_e32 v128, s84, v152
	ds_read_b128 v[164:167], v128
	ds_read_b128 v[168:171], v128 offset:1024
	ds_read_b128 v[178:181], v128 offset:2048
	ds_read_b128 v[182:185], v128 offset:3072
	s_and_b64 s[0:1], s[62:63], exec
	s_cselect_b32 s63, s61, s90
	s_cselect_b32 s62, s60, s89
	v_mov_b32_e32 v128, v146
	ds_read_b128 v[186:189], v153
	ds_read_b128 v[190:193], v153 offset:1024
	ds_read_b128 v[198:201], v153 offset:2048
	ds_read_b128 v[202:205], v153 offset:3072
	ds_read_b128 v[206:209], v153 offset:4096
	ds_read_b128 v[210:213], v153 offset:5120
	ds_read_b128 v[214:217], v153 offset:6144
	ds_read_b128 v[218:221], v153 offset:7168
	s_add_i32 m0, s68, 0xc000
	s_nop 0
	global_load_lds_dwordx4 v128, s[10:11]
	v_mov_b32_e32 v128, v148
	s_add_i32 m0, s68, 0xe000
	s_nop 0
	global_load_lds_dwordx4 v128, s[10:11]
	s_cmp_eq_u32 s99, 1
	s_cbranch_scc1 .Lmy_rw_P3_0
	s_waitcnt vmcnt(8)
	s_branch .Lmy_rd_P3_0
.Lmy_rw_P3_0:
	s_waitcnt vmcnt(24)
.Lmy_rd_P3_0:
	s_waitcnt lgkmcnt(0)
	s_barrier
	s_setprio 1
	s_waitcnt lgkmcnt(0)
	v_mfma_scale_f32_16x16x128_f8f6f4 v[112:115], v[134:141], v[186:193], v[112:115], v154, v154 op_sel_hi:[0,0,0]
	v_mfma_scale_f32_16x16x128_f8f6f4 v[116:119], v[156:163], v[186:193], v[116:119], v154, v154 op_sel_hi:[0,0,0]
	v_mfma_scale_f32_16x16x128_f8f6f4 v[96:99], v[134:141], v[198:205], v[96:99], v154, v154 op_sel_hi:[0,0,0]
	v_mfma_scale_f32_16x16x128_f8f6f4 v[100:103], v[156:163], v[198:205], v[100:103], v154, v154 op_sel_hi:[0,0,0]
	v_mfma_scale_f32_16x16x128_f8f6f4 v[142:145], v[134:141], v[206:213], v[80:83], v154, v154 op_sel_hi:[0,0,0]
	v_mfma_scale_f32_16x16x128_f8f6f4 v[172:175], v[156:163], v[206:213], v[84:87], v154, v154 op_sel_hi:[0,0,0]
	v_mfma_scale_f32_16x16x128_f8f6f4 v[194:197], v[134:141], v[214:221], v[64:67], v154, v154 op_sel_hi:[0,0,0]
	v_mfma_scale_f32_16x16x128_f8f6f4 v[222:225], v[156:163], v[214:221], v[68:71], v154, v154 op_sel_hi:[0,0,0]
	s_setprio 0
	s_setprio 1
	v_mfma_scale_f32_16x16x128_f8f6f4 v[120:123], v[164:171], v[186:193], v[120:123], v154, v154 op_sel_hi:[0,0,0]
	v_mfma_scale_f32_16x16x128_f8f6f4 v[124:127], v[178:185], v[186:193], v[124:127], v154, v154 op_sel_hi:[0,0,0]
	v_mfma_scale_f32_16x16x128_f8f6f4 v[104:107], v[164:171], v[198:205], v[104:107], v154, v154 op_sel_hi:[0,0,0]
	v_mfma_scale_f32_16x16x128_f8f6f4 v[108:111], v[178:185], v[198:205], v[108:111], v154, v154 op_sel_hi:[0,0,0]
	v_mfma_scale_f32_16x16x128_f8f6f4 v[186:189], v[164:171], v[206:213], v[88:91], v154, v154 op_sel_hi:[0,0,0]
	v_mfma_scale_f32_16x16x128_f8f6f4 v[190:193], v[178:185], v[206:213], v[92:95], v154, v154 op_sel_hi:[0,0,0]
	v_mfma_scale_f32_16x16x128_f8f6f4 v[198:201], v[164:171], v[214:221], v[72:75], v154, v154 op_sel_hi:[0,0,0]
	v_mfma_scale_f32_16x16x128_f8f6f4 v[202:205], v[178:185], v[214:221], v[76:79], v154, v154 op_sel_hi:[0,0,0]
	s_setprio 0
	s_barrier
	v_mov_b32_e32 v128, v147
	s_add_i32 s0, s52, s66
	ds_read_b128 v[64:67], v153 offset:16384
	ds_read_b128 v[68:71], v153 offset:17408
	ds_read_b128 v[72:75], v153 offset:18432
	ds_read_b128 v[76:79], v153 offset:19456
	ds_read_b128 v[80:83], v153 offset:20480
	ds_read_b128 v[84:87], v153 offset:21504
	ds_read_b128 v[88:91], v153 offset:22528
	ds_read_b128 v[92:95], v153 offset:23552
	s_mov_b32 m0, s0
	s_nop 0
	global_load_lds_dwordx4 v128, s[62:63]
	v_mov_b32_e32 v128, v149
	s_add_i32 m0, s0, 0x2000
	s_add_u32 s0, s62, 0x18000
	global_load_lds_dwordx4 v128, s[62:63]
	s_addc_u32 s1, s63, 0
	v_mov_b32_e32 v128, v147
	s_add_i32 s52, s84, s66
	s_mov_b32 m0, s52
	s_nop 0
	global_load_lds_dwordx4 v128, s[0:1]
	v_mov_b32_e32 v128, v149
	s_add_i32 m0, s52, 0x2000
	s_nop 0
	global_load_lds_dwordx4 v128, s[0:1]
	v_mov_b32_e32 v128, v146
	s_mov_b32 m0, s68
	s_nop 0
	global_load_lds_dwordx4 v128, s[64:65]
	v_mov_b32_e32 v128, v148
	s_mov_b32 m0, s69
	s_nop 0
	global_load_lds_dwordx4 v128, s[64:65]
	s_cmp_eq_u32 s99, 1
	s_cbranch_scc1 .Lmy_rw_P3_1
	s_waitcnt vmcnt(8)
	s_branch .Lmy_rd_P3_1

; #define PG8_STAGE(bufoff, gbase, voff) do { _Pragma("unroll") for (int _i = 0; _i < 2; ++_i) { unsigned vo_ = (voff)[_i]; if constexpr (FP8) asm volatile("" : "+v"(vo_)); \
;         __builtin_amdgcn_global_load_lds((const unsigned*)((const char*)(gbase) + vo_), (PG8_LAS unsigned*)(lds + (bufoff) + ldsw + _i * 8192), 16, 0, 0); } } while (0)
; #define PG8_LDA(dst, b, h) do { _Pragma("unroll") for (int m = 0; m < 4; ++m) _Pragma("unroll") for (int k = 0; k < 2; ++k) dst[m][k] = *(const PG8_LAS bf16x8*)(lds + PG8_SA(b, h) + aoff + m * 2048 + k * 1024); } while (0)
; #define PG8_LDB(dst, b, h) do { _Pragma("unroll") for (int n = 0; n < 2; ++n) _Pragma("unroll") for (int k = 0; k < 2; ++k) dst[n][k] = *(const PG8_LAS bf16x8*)(lds + PG8_SB(b, h) + boff + n * 2048 + k * 1024); } while (0)
; #define PG8_WAIT_V(n) asm volatile("s_waitcnt vmcnt(" #n ")" ::: "memory")
; #define PG8_WAIT_L(n) asm volatile("s_waitcnt lgkmcnt(" #n ")" ::: "memory")
; #define PG8_BAR __builtin_amdgcn_s_barrier()
; #define PG8_SCHED __builtin_amdgcn_sched_barrier(0)
; template <class Epi, class Sched, bool ALIGN_EPI = false, bool SP2 = false, bool FP8 = false>
; __device__ __forceinline__ void gemm_phase(PG8_LAS unsigned char* lds, const Gemm g, const Sched& S, const Epi& E) {
;     ...
;             PG8_WAIT_V(8); PG8_WAIT_L(0); PG8_BAR; PG8_MMA(1, 0, At, B0); PG8_MMA(1, 1, At, B1); PG8_BAR; PG8_SCHED;
;             PG8_LDB(B0, 1, 0); PG8_LDB(B1, 1, 1); PG8_SCHED; PG8_LDA(At, 1, 0); PG8_STAGE(PG8_SA(0, 1), a2 + hstep, voffA);
;             PG8_WAIT_V(8); PG8_WAIT_L(0); PG8_BAR; PG8_MMA(0, 0, At, B0); PG8_MMA(0, 1, At, B1); PG8_BAR; PG8_SCHED;
;             PG8_LDA(At, 1, 1); PG8_STAGE(PG8_SB(1, 0), b3, voffB); PG8_STAGE(PG8_SB(1, 1), b3 + hstep, voffB); PG8_STAGE(PG8_SA(1, 0), a3, voffA);
.Lmy_rd_P3_1:
	s_mov_b32 s99, 0
	s_waitcnt lgkmcnt(0)
	s_barrier
	s_setprio 1
	s_waitcnt lgkmcnt(0)
	v_mfma_scale_f32_16x16x128_f8f6f4 v[48:51], v[134:141], v[64:71], v[48:51], v154, v154 op_sel_hi:[0,0,0]
	v_mfma_scale_f32_16x16x128_f8f6f4 v[52:55], v[156:163], v[64:71], v[52:55], v154, v154 op_sel_hi:[0,0,0]
	v_mfma_scale_f32_16x16x128_f8f6f4 v[206:209], v[134:141], v[72:79], v[32:35], v154, v154 op_sel_hi:[0,0,0]
	v_mfma_scale_f32_16x16x128_f8f6f4 v[210:213], v[156:163], v[72:79], v[36:39], v154, v154 op_sel_hi:[0,0,0]
	v_mfma_scale_f32_16x16x128_f8f6f4 v[214:217], v[134:141], v[80:87], v[16:19], v154, v154 op_sel_hi:[0,0,0]
	v_mfma_scale_f32_16x16x128_f8f6f4 v[218:221], v[156:163], v[80:87], v[20:23], v154, v154 op_sel_hi:[0,0,0]
	v_mfma_scale_f32_16x16x128_f8f6f4 v[226:229], v[134:141], v[88:95], v[4:7], v154, v154 op_sel_hi:[0,0,0]
	v_mfma_scale_f32_16x16x128_f8f6f4 v[230:233], v[156:163], v[88:95], v[8:11], v154, v154 op_sel_hi:[0,0,0]
	s_setprio 0
	s_setprio 1
	v_mfma_scale_f32_16x16x128_f8f6f4 v[56:59], v[164:171], v[64:71], v[56:59], v154, v154 op_sel_hi:[0,0,0]
	v_mfma_scale_f32_16x16x128_f8f6f4 v[60:63], v[178:185], v[64:71], v[60:63], v154, v154 op_sel_hi:[0,0,0]
	v_mfma_scale_f32_16x16x128_f8f6f4 v[234:237], v[164:171], v[72:79], v[40:43], v154, v154 op_sel_hi:[0,0,0]
	v_mfma_scale_f32_16x16x128_f8f6f4 v[238:241], v[178:185], v[72:79], v[44:47], v154, v154 op_sel_hi:[0,0,0]
	v_mfma_scale_f32_16x16x128_f8f6f4 v[242:245], v[164:171], v[80:87], v[24:27], v154, v154 op_sel_hi:[0,0,0]
	v_mfma_scale_f32_16x16x128_f8f6f4 v[246:249], v[178:185], v[80:87], v[28:31], v154, v154 op_sel_hi:[0,0,0]
	v_mfma_scale_f32_16x16x128_f8f6f4 v[250:253], v[164:171], v[88:95], v[12:15], v154, v154 op_sel_hi:[0,0,0]
	v_mfma_scale_f32_16x16x128_f8f6f4 v[130:133], v[178:185], v[88:95], v[0:3], v154, v154 op_sel_hi:[0,0,0]
	s_setprio 0
	s_barrier
	s_add_i32 s52, 0, 0x18000
	s_add_i32 s53, 0, 0x1c000
	s_nop 1
	v_add_u32_e32 v12, s52, v152
	v_add_u32_e32 v16, s53, v152
	ds_read_b128 v[0:3], v12
	ds_read_b128 v[4:7], v12 offset:1024
	ds_read_b128 v[8:11], v12 offset:2048
	ds_read_b128 v[12:15], v12 offset:3072
	ds_read_b128 v[134:137], v16
	ds_read_b128 v[138:141], v16 offset:1024
	ds_read_b128 v[156:159], v16 offset:2048
	ds_read_b128 v[160:163], v16 offset:3072
	s_add_u32 s0, s64, 0x18000
	v_mov_b32_e32 v64, v146
	s_mov_b32 m0, s70
	ds_read_b128 v[16:19], v153 offset:32768
	ds_read_b128 v[20:23], v153 offset:33792
	ds_read_b128 v[24:27], v153 offset:34816
	ds_read_b128 v[28:31], v153 offset:35840
	ds_read_b128 v[32:35], v153 offset:36864
	ds_read_b128 v[36:39], v153 offset:37888
	ds_read_b128 v[40:43], v153 offset:38912
	ds_read_b128 v[44:47], v153 offset:39936
	s_addc_u32 s1, s65, 0
	s_nop 0
	global_load_lds_dwordx4 v64, s[0:1]
	v_mov_b32_e32 v64, v148
	s_mov_b32 m0, s71
	s_nop 0
	global_load_lds_dwordx4 v64, s[0:1]
	s_waitcnt vmcnt(8)
	s_waitcnt lgkmcnt(0)
	s_barrier
	s_setprio 1
	s_waitcnt lgkmcnt(0)
	v_mfma_scale_f32_16x16x128_f8f6f4 v[112:115], v[0:7], v[16:23], v[112:115], v154, v154 op_sel_hi:[0,0,0]
	v_mfma_scale_f32_16x16x128_f8f6f4 v[116:119], v[8:15], v[16:23], v[116:119], v154, v154 op_sel_hi:[0,0,0]
	v_mfma_scale_f32_16x16x128_f8f6f4 v[96:99], v[0:7], v[24:31], v[96:99], v154, v154 op_sel_hi:[0,0,0]
	v_mfma_scale_f32_16x16x128_f8f6f4 v[100:103], v[8:15], v[24:31], v[100:103], v154, v154 op_sel_hi:[0,0,0]
	v_mfma_scale_f32_16x16x128_f8f6f4 v[80:83], v[0:7], v[32:39], v[142:145], v154, v154 op_sel_hi:[0,0,0]
	v_mfma_scale_f32_16x16x128_f8f6f4 v[84:87], v[8:15], v[32:39], v[172:175], v154, v154 op_sel_hi:[0,0,0]
	v_mfma_scale_f32_16x16x128_f8f6f4 v[64:67], v[0:7], v[40:47], v[194:197], v154, v154 op_sel_hi:[0,0,0]
	v_mfma_scale_f32_16x16x128_f8f6f4 v[68:71], v[8:15], v[40:47], v[222:225], v154, v154 op_sel_hi:[0,0,0]
	s_setprio 0
	s_setprio 1
	v_mfma_scale_f32_16x16x128_f8f6f4 v[120:123], v[134:141], v[16:23], v[120:123], v154, v154 op_sel_hi:[0,0,0]
	v_mfma_scale_f32_16x16x128_f8f6f4 v[124:127], v[156:163], v[16:23], v[124:127], v154, v154 op_sel_hi:[0,0,0]
	v_mfma_scale_f32_16x16x128_f8f6f4 v[104:107], v[134:141], v[24:31], v[104:107], v154, v154 op_sel_hi:[0,0,0]
	v_mfma_scale_f32_16x16x128_f8f6f4 v[108:111], v[156:163], v[24:31], v[108:111], v154, v154 op_sel_hi:[0,0,0]
	v_mfma_scale_f32_16x16x128_f8f6f4 v[88:91], v[134:141], v[32:39], v[186:189], v154, v154 op_sel_hi:[0,0,0]
	v_mfma_scale_f32_16x16x128_f8f6f4 v[92:95], v[156:163], v[32:39], v[190:193], v154, v154 op_sel_hi:[0,0,0]
	v_mfma_scale_f32_16x16x128_f8f6f4 v[72:75], v[134:141], v[40:47], v[198:201], v154, v154 op_sel_hi:[0,0,0]
	v_mfma_scale_f32_16x16x128_f8f6f4 v[76:79], v[156:163], v[40:47], v[202:205], v154, v154 op_sel_hi:[0,0,0]
	s_setprio 0
	s_barrier
; #define PG8_STAGE(bufoff, gbase, voff) do { _Pragma("unroll") for (int _i = 0; _i < 2; ++_i) { unsigned vo_ = (voff)[_i]; if constexpr (FP8) asm volatile("" : "+v"(vo_)); \
;         __builtin_amdgcn_global_load_lds((const unsigned*)((const char*)(gbase) + vo_), (PG8_LAS unsigned*)(lds + (bufoff) + ldsw + _i * 8192), 16, 0, 0); } } while (0)
; #define PG8_LDA(dst, b, h) do { _Pragma("unroll") for (int m = 0; m < 4; ++m) _Pragma("unroll") for (int k = 0; k < 2; ++k) dst[m][k] = *(const PG8_LAS bf16x8*)(lds + PG8_SA(b, h) + aoff + m * 2048 + k * 1024); } while (0)
; #define PG8_WAIT_V(n) asm volatile("s_waitcnt vmcnt(" #n ")" ::: "memory")
; #define PG8_WAIT_L(n) asm volatile("s_waitcnt lgkmcnt(" #n ")" ::: "memory")
; #define PG8_BAR __builtin_amdgcn_s_barrier()
; #define PG8_SCHED __builtin_amdgcn_sched_barrier(0)
; template <class Epi, class Sched, bool ALIGN_EPI = false, bool SP2 = false, bool FP8 = false>
; __device__ __forceinline__ void gemm_phase(PG8_LAS unsigned char* lds, const Gemm g, const Sched& S, const Epi& E) {
;     ...
;             PG8_LDA(At, 1, 1); PG8_STAGE(PG8_SB(1, 0), b3, voffB); PG8_STAGE(PG8_SB(1, 1), b3 + hstep, voffB); PG8_STAGE(PG8_SA(1, 0), a3, voffA);
;             PG8_WAIT_V(8); PG8_WAIT_L(0); PG8_BAR; PG8_MMA(1, 0, At, B0); PG8_MMA(1, 1, At, B1); PG8_BAR; PG8_SCHED;
	v_mov_b32_e32 v128, v147
	ds_read_b128 v[24:27], v153 offset:49152
	ds_read_b128 v[28:31], v153 offset:50176
	ds_read_b128 v[164:167], v153 offset:51200
	ds_read_b128 v[168:171], v153 offset:52224
	ds_read_b128 v[178:181], v153 offset:53248
	ds_read_b128 v[182:185], v153 offset:54272
	ds_read_b128 v[186:189], v153 offset:55296
	ds_read_b128 v[190:193], v153 offset:56320
	s_add_i32 s0, s52, s66
	v_lshl_add_u64 v[16:17], s[62:63], 0, v[128:129]
	v_lshl_add_u64 v[16:17], v[16:17], 0, s[40:41]
	s_mov_b32 m0, s0
	v_mov_b32_e32 v128, v149
	global_load_lds_dwordx4 v[16:17], off
	s_add_i32 m0, s0, 0x2000
	v_lshl_add_u64 v[16:17], s[62:63], 0, v[128:129]
	v_lshl_add_u64 v[16:17], v[16:17], 0, s[40:41]
	s_add_u32 s0, s62, 0x18080
	global_load_lds_dwordx4 v[16:17], off
	s_addc_u32 s1, s63, 0
	v_mov_b32_e32 v16, v147
	s_add_i32 s52, s53, s66
	s_mov_b32 m0, s52
	v_mov_b32_e32 v128, v146
	global_load_lds_dwordx4 v16, s[0:1]
	v_mov_b32_e32 v16, v149
	s_add_i32 m0, s52, 0x2000
	s_nop 0
	global_load_lds_dwordx4 v16, s[0:1]
	s_mov_b32 m0, s75
	v_lshl_add_u64 v[16:17], s[64:65], 0, v[128:129]
	v_lshl_add_u64 v[16:17], v[16:17], 0, s[40:41]
	v_mov_b32_e32 v128, v148
	global_load_lds_dwordx4 v[16:17], off
	s_mov_b32 m0, s77
	v_lshl_add_u64 v[16:17], s[64:65], 0, v[128:129]
	v_lshl_add_u64 v[16:17], v[16:17], 0, s[40:41]
	global_load_lds_dwordx4 v[16:17], off
	s_waitcnt vmcnt(8)
	s_waitcnt lgkmcnt(0)
	s_barrier
	s_setprio 1
	s_waitcnt lgkmcnt(0)
	v_mfma_scale_f32_16x16x128_f8f6f4 v[48:51], v[0:7], v[24:31], v[48:51], v154, v154 op_sel_hi:[0,0,0]
	v_mfma_scale_f32_16x16x128_f8f6f4 v[52:55], v[8:15], v[24:31], v[52:55], v154, v154 op_sel_hi:[0,0,0]
	v_mfma_scale_f32_16x16x128_f8f6f4 v[32:35], v[0:7], v[164:171], v[206:209], v154, v154 op_sel_hi:[0,0,0]
	v_mfma_scale_f32_16x16x128_f8f6f4 v[36:39], v[8:15], v[164:171], v[210:213], v154, v154 op_sel_hi:[0,0,0]
	v_mfma_scale_f32_16x16x128_f8f6f4 v[16:19], v[0:7], v[178:185], v[214:217], v154, v154 op_sel_hi:[0,0,0]
	v_mfma_scale_f32_16x16x128_f8f6f4 v[20:23], v[8:15], v[178:185], v[218:221], v154, v154 op_sel_hi:[0,0,0]
	v_mfma_scale_f32_16x16x128_f8f6f4 v[4:7], v[0:7], v[186:193], v[226:229], v154, v154 op_sel_hi:[0,0,0]
	v_mfma_scale_f32_16x16x128_f8f6f4 v[8:11], v[8:15], v[186:193], v[230:233], v154, v154 op_sel_hi:[0,0,0]
	s_setprio 0
	s_setprio 1
	v_mfma_scale_f32_16x16x128_f8f6f4 v[56:59], v[134:141], v[24:31], v[56:59], v154, v154 op_sel_hi:[0,0,0]
	v_mfma_scale_f32_16x16x128_f8f6f4 v[60:63], v[156:163], v[24:31], v[60:63], v154, v154 op_sel_hi:[0,0,0]
	v_mfma_scale_f32_16x16x128_f8f6f4 v[40:43], v[134:141], v[164:171], v[234:237], v154, v154 op_sel_hi:[0,0,0]
	v_mfma_scale_f32_16x16x128_f8f6f4 v[44:47], v[156:163], v[164:171], v[238:241], v154, v154 op_sel_hi:[0,0,0]
	v_mfma_scale_f32_16x16x128_f8f6f4 v[24:27], v[134:141], v[178:185], v[242:245], v154, v154 op_sel_hi:[0,0,0]
	v_mfma_scale_f32_16x16x128_f8f6f4 v[28:31], v[156:163], v[178:185], v[246:249], v154, v154 op_sel_hi:[0,0,0]
	v_mfma_scale_f32_16x16x128_f8f6f4 v[12:15], v[134:141], v[186:193], v[250:253], v154, v154 op_sel_hi:[0,0,0]
	v_mfma_scale_f32_16x16x128_f8f6f4 v[0:3], v[156:163], v[186:193], v[130:133], v154, v154 op_sel_hi:[0,0,0]
	s_setprio 0
	s_barrier
	s_add_i32 s91, s91, 2
	s_add_u32 s10, s10, 0x100
	s_addc_u32 s11, s11, 0
	s_add_u32 s89, s89, 0x100
	s_addc_u32 s90, s90, 0
	s_cmp_gt_u32 s91, 3
	s_cbranch_scc1 .LBB0_308

; template <class Epi, class Sched, bool ALIGN_EPI = false, bool SP2 = false, bool FP8 = false>
; __device__ __forceinline__ void gemm_phase(PG8_LAS unsigned char* lds, const Gemm g, const Sched& S, const Epi& E) {
;     ...
;     for (;;) {
;         const bool has_next = S.next(ui + 1, nxt);
;         const char* nA = has_next ? (const char*)g.A + (size_t)nxt.pm * tstep : cA; const char* nB = has_next ? (const char*)g.Bt + (size_t)nxt.pn * tstep : cB;
; #pragma unroll 1
;         for (int t = 0; t < nt; t += 2) {
.LBB0_337:
	s_mov_b32 s99, 1
	s_mov_b64 s[4:5], 0

; #define PG8_STAGE(bufoff, gbase, voff) do { _Pragma("unroll") for (int _i = 0; _i < 2; ++_i) { unsigned vo_ = (voff)[_i]; if constexpr (FP8) asm volatile("" : "+v"(vo_)); \
;         __builtin_amdgcn_global_load_lds((const unsigned*)((const char*)(gbase) + vo_), (PG8_LAS unsigned*)(lds + (bufoff) + ldsw + _i * 8192), 16, 0, 0); } } while (0)
; #define PG8_LDA(dst, b, h) do { _Pragma("unroll") for (int m = 0; m < 4; ++m) _Pragma("unroll") for (int k = 0; k < 2; ++k) dst[m][k] = *(const PG8_LAS bf16x8*)(lds + PG8_SA(b, h) + aoff + m * 2048 + k * 1024); } while (0)
; #define PG8_LDB(dst, b, h) do { _Pragma("unroll") for (int n = 0; n < 2; ++n) _Pragma("unroll") for (int k = 0; k < 2; ++k) dst[n][k] = *(const PG8_LAS bf16x8*)(lds + PG8_SB(b, h) + boff + n * 2048 + k * 1024); } while (0)
; #define PG8_WAIT_V(n) asm volatile("s_waitcnt vmcnt(" #n ")" ::: "memory")
; #define PG8_WAIT_L(n) asm volatile("s_waitcnt lgkmcnt(" #n ")" ::: "memory")
; #define PG8_BAR __builtin_amdgcn_s_barrier()
; #define PG8_SCHED __builtin_amdgcn_sched_barrier(0)
; template <class Epi, class Sched, bool ALIGN_EPI = false, bool SP2 = false, bool FP8 = false>
; __device__ __forceinline__ void gemm_phase(PG8_LAS unsigned char* lds, const Gemm g, const Sched& S, const Epi& E) {
;     ...
;             PG8_LDB(B0, 0, 0); PG8_LDB(B1, 0, 1); PG8_SCHED; PG8_LDA(At, 0, 0); PG8_STAGE(PG8_SA(1, 1), a1 + hstep, voffA);
;             PG8_WAIT_V(8); PG8_WAIT_L(0); PG8_BAR; PG8_MMA(0, 0, At, B0); PG8_MMA(0, 1, At, B1); PG8_BAR; PG8_SCHED;
;             PG8_LDA(At, 0, 1); PG8_STAGE(PG8_SB(0, 0), b2, voffB); PG8_STAGE(PG8_SB(0, 1), b2 + hstep, voffB); PG8_STAGE(PG8_SA(0, 0), a2, voffA);
;             PG8_WAIT_V(8); PG8_WAIT_L(0); PG8_BAR; PG8_MMA(1, 0, At, B0); PG8_MMA(1, 1, At, B1); PG8_BAR; PG8_SCHED;
.Lmy_nobar_P4:
.LBB0_342:
	v_add_u32_e32 v140, s69, v201
	v_add_u32_e32 v156, s70, v201
	ds_read_b128 v[128:131], v140
	ds_read_b128 v[132:135], v140 offset:1024
	ds_read_b128 v[136:139], v140 offset:2048
	ds_read_b128 v[140:143], v140 offset:3072
	ds_read_b128 v[144:147], v156
	ds_read_b128 v[148:151], v156 offset:1024
	ds_read_b128 v[152:155], v156 offset:2048
	ds_read_b128 v[156:159], v156 offset:3072
	s_add_u32 s0, s10, 0xfffe0080
	s_addc_u32 s1, s11, -1
	s_cmp_eq_u32 s74, 4
	s_cselect_b32 s55, s9, s1
	s_cselect_b32 s54, s45, s0
	s_cselect_b32 s57, s43, s73
	s_cselect_b32 s56, s51, s72
	v_mov_b32_e32 v178, v197
	ds_read_b128 v[160:163], v202
	ds_read_b128 v[164:167], v202 offset:1024
	ds_read_b128 v[168:171], v202 offset:2048
	ds_read_b128 v[172:175], v202 offset:3072
	ds_read_b128 v[184:187], v202 offset:4096
	ds_read_b128 v[188:191], v202 offset:5120
	ds_read_b128 v[206:209], v202 offset:6144
	ds_read_b128 v[210:213], v202 offset:7168
	s_add_i32 m0, s53, 0xc000
	s_nop 0
	global_load_lds_dwordx4 v178, s[10:11]
	v_mov_b32_e32 v178, v199
	s_add_i32 m0, s53, 0xe000
	s_nop 0
	global_load_lds_dwordx4 v178, s[10:11]
	s_cmp_eq_u32 s99, 1
	s_cbranch_scc1 .Lmy_rw_P4_0
	s_waitcnt vmcnt(8)
	s_branch .Lmy_rd_P4_0
.Lmy_rw_P4_0:
	s_waitcnt vmcnt(32)
.Lmy_rd_P4_0:
	s_waitcnt lgkmcnt(0)
	s_barrier
	s_setprio 1
	s_waitcnt lgkmcnt(0)
	v_mfma_scale_f32_16x16x128_f8f6f4 v[116:119], v[128:135], v[160:167], v[116:119], v203, v203 op_sel_hi:[0,0,0]
	v_mfma_scale_f32_16x16x128_f8f6f4 v[112:115], v[136:143], v[160:167], v[112:115], v203, v203 op_sel_hi:[0,0,0]
	v_mfma_scale_f32_16x16x128_f8f6f4 v[108:111], v[128:135], v[168:175], v[108:111], v203, v203 op_sel_hi:[0,0,0]
	v_mfma_scale_f32_16x16x128_f8f6f4 v[100:103], v[136:143], v[168:175], v[100:103], v203, v203 op_sel_hi:[0,0,0]
	v_mfma_scale_f32_16x16x128_f8f6f4 v[192:195], v[128:135], v[184:191], v[92:95], v203, v203 op_sel_hi:[0,0,0]
	v_mfma_scale_f32_16x16x128_f8f6f4 v[214:217], v[136:143], v[184:191], v[84:87], v203, v203 op_sel_hi:[0,0,0]
	v_mfma_scale_f32_16x16x128_f8f6f4 v[218:221], v[128:135], v[206:213], v[76:79], v203, v203 op_sel_hi:[0,0,0]
	v_mfma_scale_f32_16x16x128_f8f6f4 v[222:225], v[136:143], v[206:213], v[68:71], v203, v203 op_sel_hi:[0,0,0]
	s_setprio 0
	s_setprio 1
	v_mfma_scale_f32_16x16x128_f8f6f4 v[124:127], v[144:151], v[160:167], v[124:127], v203, v203 op_sel_hi:[0,0,0]
	v_mfma_scale_f32_16x16x128_f8f6f4 v[120:123], v[152:159], v[160:167], v[120:123], v203, v203 op_sel_hi:[0,0,0]
	v_mfma_scale_f32_16x16x128_f8f6f4 v[104:107], v[144:151], v[168:175], v[104:107], v203, v203 op_sel_hi:[0,0,0]
	v_mfma_scale_f32_16x16x128_f8f6f4 v[96:99], v[152:159], v[168:175], v[96:99], v203, v203 op_sel_hi:[0,0,0]
	v_mfma_scale_f32_16x16x128_f8f6f4 v[160:163], v[144:151], v[184:191], v[88:91], v203, v203 op_sel_hi:[0,0,0]
	v_mfma_scale_f32_16x16x128_f8f6f4 v[164:167], v[152:159], v[184:191], v[80:83], v203, v203 op_sel_hi:[0,0,0]
	v_mfma_scale_f32_16x16x128_f8f6f4 v[168:171], v[144:151], v[206:213], v[72:75], v203, v203 op_sel_hi:[0,0,0]
	v_mfma_scale_f32_16x16x128_f8f6f4 v[172:175], v[152:159], v[206:213], v[64:67], v203, v203 op_sel_hi:[0,0,0]
	s_setprio 0
	s_barrier
	v_mov_b32_e32 v178, v198
	s_add_i32 s0, s69, s41
	s_nop 2
	ds_read_b128 v[64:67], v202 offset:16384
	ds_read_b128 v[68:71], v202 offset:17408
	ds_read_b128 v[72:75], v202 offset:18432
	ds_read_b128 v[76:79], v202 offset:19456
	ds_read_b128 v[80:83], v202 offset:20480
	ds_read_b128 v[84:87], v202 offset:21504
	ds_read_b128 v[88:91], v202 offset:22528
	ds_read_b128 v[92:95], v202 offset:23552
	s_mov_b32 m0, s0
	s_nop 0
	global_load_lds_dwordx4 v178, s[56:57]
	v_mov_b32_e32 v178, v200
	s_add_i32 m0, s0, 0x2000
	s_add_u32 s0, s56, 0x20000
	global_load_lds_dwordx4 v178, s[56:57]
	s_addc_u32 s1, s57, 0
	v_mov_b32_e32 v178, v198
	s_add_i32 s75, s70, s41
	s_mov_b32 m0, s75
	s_nop 0
	global_load_lds_dwordx4 v178, s[0:1]
	v_mov_b32_e32 v178, v200
	s_add_i32 m0, s75, 0x2000
	s_nop 0
	global_load_lds_dwordx4 v178, s[0:1]
	v_mov_b32_e32 v178, v197
	s_mov_b32 m0, s53
	s_nop 0
	global_load_lds_dwordx4 v178, s[54:55]
	v_mov_b32_e32 v178, v199
	s_mov_b32 m0, s58
	s_nop 0
	global_load_lds_dwordx4 v178, s[54:55]
	s_cmp_eq_u32 s99, 1
	s_cbranch_scc1 .Lmy_rw_P4_1
	s_waitcnt vmcnt(8)
	s_branch .Lmy_rd_P4_1

; #define PG8_STAGE(bufoff, gbase, voff) do { _Pragma("unroll") for (int _i = 0; _i < 2; ++_i) { unsigned vo_ = (voff)[_i]; if constexpr (FP8) asm volatile("" : "+v"(vo_)); \
;         __builtin_amdgcn_global_load_lds((const unsigned*)((const char*)(gbase) + vo_), (PG8_LAS unsigned*)(lds + (bufoff) + ldsw + _i * 8192), 16, 0, 0); } } while (0)
; #define PG8_LDA(dst, b, h) do { _Pragma("unroll") for (int m = 0; m < 4; ++m) _Pragma("unroll") for (int k = 0; k < 2; ++k) dst[m][k] = *(const PG8_LAS bf16x8*)(lds + PG8_SA(b, h) + aoff + m * 2048 + k * 1024); } while (0)
; #define PG8_LDB(dst, b, h) do { _Pragma("unroll") for (int n = 0; n < 2; ++n) _Pragma("unroll") for (int k = 0; k < 2; ++k) dst[n][k] = *(const PG8_LAS bf16x8*)(lds + PG8_SB(b, h) + boff + n * 2048 + k * 1024); } while (0)
; #define PG8_WAIT_V(n) asm volatile("s_waitcnt vmcnt(" #n ")" ::: "memory")
; #define PG8_WAIT_L(n) asm volatile("s_waitcnt lgkmcnt(" #n ")" ::: "memory")
; #define PG8_BAR __builtin_amdgcn_s_barrier()
; #define PG8_SCHED __builtin_amdgcn_sched_barrier(0)
; template <class Epi, class Sched, bool ALIGN_EPI = false, bool SP2 = false, bool FP8 = false>
; __device__ __forceinline__ void gemm_phase(PG8_LAS unsigned char* lds, const Gemm g, const Sched& S, const Epi& E) {
;     ...
;             PG8_WAIT_V(8); PG8_WAIT_L(0); PG8_BAR; PG8_MMA(1, 0, At, B0); PG8_MMA(1, 1, At, B1); PG8_BAR; PG8_SCHED;
;             PG8_LDB(B0, 1, 0); PG8_LDB(B1, 1, 1); PG8_SCHED; PG8_LDA(At, 1, 0); PG8_STAGE(PG8_SA(0, 1), a2 + hstep, voffA);
;             PG8_WAIT_V(8); PG8_WAIT_L(0); PG8_BAR; PG8_MMA(0, 0, At, B0); PG8_MMA(0, 1, At, B1); PG8_BAR; PG8_SCHED;
;             PG8_LDA(At, 1, 1); PG8_STAGE(PG8_SB(1, 0), b3, voffB); PG8_STAGE(PG8_SB(1, 1), b3 + hstep, voffB); PG8_STAGE(PG8_SA(1, 0), a3, voffA);
.Lmy_rd_P4_1:
	s_mov_b32 s99, 0
	s_waitcnt lgkmcnt(0)
	s_barrier
	s_setprio 1
	s_waitcnt lgkmcnt(0)
	v_mfma_scale_f32_16x16x128_f8f6f4 v[52:55], v[128:135], v[64:71], v[52:55], v203, v203 op_sel_hi:[0,0,0]
	v_mfma_scale_f32_16x16x128_f8f6f4 v[48:51], v[136:143], v[64:71], v[48:51], v203, v203 op_sel_hi:[0,0,0]
	v_mfma_scale_f32_16x16x128_f8f6f4 v[44:47], v[128:135], v[72:79], v[44:47], v203, v203 op_sel_hi:[0,0,0]
	v_mfma_scale_f32_16x16x128_f8f6f4 v[184:187], v[136:143], v[72:79], v[36:39], v203, v203 op_sel_hi:[0,0,0]
	v_mfma_scale_f32_16x16x128_f8f6f4 v[188:191], v[128:135], v[80:87], v[28:31], v203, v203 op_sel_hi:[0,0,0]
	v_mfma_scale_f32_16x16x128_f8f6f4 v[206:209], v[136:143], v[80:87], v[20:23], v203, v203 op_sel_hi:[0,0,0]
	v_mfma_scale_f32_16x16x128_f8f6f4 v[210:213], v[128:135], v[88:95], v[12:15], v203, v203 op_sel_hi:[0,0,0]
	v_mfma_scale_f32_16x16x128_f8f6f4 v[226:229], v[136:143], v[88:95], v[4:7], v203, v203 op_sel_hi:[0,0,0]
	s_setprio 0
	s_setprio 1
	v_mfma_scale_f32_16x16x128_f8f6f4 v[40:43], v[144:151], v[72:79], v[40:43], v203, v203 op_sel_hi:[0,0,0]
	v_mfma_scale_f32_16x16x128_f8f6f4 v[230:233], v[144:151], v[64:71], v[60:63], v203, v203 op_sel_hi:[0,0,0]
	v_mfma_scale_f32_16x16x128_f8f6f4 v[234:237], v[152:159], v[64:71], v[56:59], v203, v203 op_sel_hi:[0,0,0]
	v_mfma_scale_f32_16x16x128_f8f6f4 v[238:241], v[152:159], v[72:79], v[32:35], v203, v203 op_sel_hi:[0,0,0]
	v_mfma_scale_f32_16x16x128_f8f6f4 v[242:245], v[144:151], v[80:87], v[24:27], v203, v203 op_sel_hi:[0,0,0]
	v_mfma_scale_f32_16x16x128_f8f6f4 v[246:249], v[152:159], v[80:87], v[16:19], v203, v203 op_sel_hi:[0,0,0]
	v_mfma_scale_f32_16x16x128_f8f6f4 v[250:253], v[144:151], v[88:95], v[8:11], v203, v203 op_sel_hi:[0,0,0]
	v_mfma_scale_f32_16x16x128_f8f6f4 v[180:183], v[152:159], v[88:95], v[0:3], v203, v203 op_sel_hi:[0,0,0]
	s_setprio 0
	s_barrier
	s_add_i32 s75, 0, 0x18000
	s_nop 2
	v_add_u32_e32 v8, s75, v201
	s_add_i32 s77, 0, 0x1c000
	ds_read_b128 v[0:3], v8
	ds_read_b128 v[4:7], v8 offset:1024
	ds_read_b128 v[56:59], v8 offset:2048
	ds_read_b128 v[60:63], v8 offset:3072
	v_add_u32_e32 v8, s77, v201
	ds_read_b128 v[128:131], v8
	ds_read_b128 v[132:135], v8 offset:1024
	ds_read_b128 v[136:139], v8 offset:2048
	ds_read_b128 v[140:143], v8 offset:3072
	s_add_u32 s0, s54, 0x20000
	v_mov_b32_e32 v64, v197
	s_mov_b32 m0, s59
	ds_read_b128 v[8:11], v202 offset:32768
	ds_read_b128 v[12:15], v202 offset:33792
	ds_read_b128 v[16:19], v202 offset:34816
	ds_read_b128 v[20:23], v202 offset:35840
	ds_read_b128 v[24:27], v202 offset:36864
	ds_read_b128 v[28:31], v202 offset:37888
	ds_read_b128 v[32:35], v202 offset:38912
	ds_read_b128 v[36:39], v202 offset:39936
	s_addc_u32 s1, s55, 0
	s_nop 0
	global_load_lds_dwordx4 v64, s[0:1]
	v_mov_b32_e32 v64, v199
	s_mov_b32 m0, s60
	s_nop 0
	global_load_lds_dwordx4 v64, s[0:1]
	s_waitcnt vmcnt(8)
	s_waitcnt lgkmcnt(0)
	s_barrier
	s_setprio 1
	s_waitcnt lgkmcnt(0)
	v_mfma_scale_f32_16x16x128_f8f6f4 v[116:119], v[0:7], v[8:15], v[116:119], v203, v203 op_sel_hi:[0,0,0]
	v_mfma_scale_f32_16x16x128_f8f6f4 v[112:115], v[56:63], v[8:15], v[112:115], v203, v203 op_sel_hi:[0,0,0]
	v_mfma_scale_f32_16x16x128_f8f6f4 v[108:111], v[0:7], v[16:23], v[108:111], v203, v203 op_sel_hi:[0,0,0]
	v_mfma_scale_f32_16x16x128_f8f6f4 v[100:103], v[56:63], v[16:23], v[100:103], v203, v203 op_sel_hi:[0,0,0]
	v_mfma_scale_f32_16x16x128_f8f6f4 v[92:95], v[0:7], v[24:31], v[192:195], v203, v203 op_sel_hi:[0,0,0]
	v_mfma_scale_f32_16x16x128_f8f6f4 v[84:87], v[56:63], v[24:31], v[214:217], v203, v203 op_sel_hi:[0,0,0]
	v_mfma_scale_f32_16x16x128_f8f6f4 v[76:79], v[0:7], v[32:39], v[218:221], v203, v203 op_sel_hi:[0,0,0]
	v_mfma_scale_f32_16x16x128_f8f6f4 v[68:71], v[56:63], v[32:39], v[222:225], v203, v203 op_sel_hi:[0,0,0]
	s_setprio 0
	s_setprio 1
	v_mfma_scale_f32_16x16x128_f8f6f4 v[124:127], v[128:135], v[8:15], v[124:127], v203, v203 op_sel_hi:[0,0,0]
	v_mfma_scale_f32_16x16x128_f8f6f4 v[120:123], v[136:143], v[8:15], v[120:123], v203, v203 op_sel_hi:[0,0,0]
	v_mfma_scale_f32_16x16x128_f8f6f4 v[104:107], v[128:135], v[16:23], v[104:107], v203, v203 op_sel_hi:[0,0,0]
	v_mfma_scale_f32_16x16x128_f8f6f4 v[96:99], v[136:143], v[16:23], v[96:99], v203, v203 op_sel_hi:[0,0,0]
	v_mfma_scale_f32_16x16x128_f8f6f4 v[88:91], v[128:135], v[24:31], v[160:163], v203, v203 op_sel_hi:[0,0,0]
	v_mfma_scale_f32_16x16x128_f8f6f4 v[80:83], v[136:143], v[24:31], v[164:167], v203, v203 op_sel_hi:[0,0,0]
	v_mfma_scale_f32_16x16x128_f8f6f4 v[72:75], v[128:135], v[32:39], v[168:171], v203, v203 op_sel_hi:[0,0,0]
	v_mfma_scale_f32_16x16x128_f8f6f4 v[64:67], v[136:143], v[32:39], v[172:175], v203, v203 op_sel_hi:[0,0,0]
	s_setprio 0
	s_barrier
; #define PG8_STAGE(bufoff, gbase, voff) do { _Pragma("unroll") for (int _i = 0; _i < 2; ++_i) { unsigned vo_ = (voff)[_i]; if constexpr (FP8) asm volatile("" : "+v"(vo_)); \
;         __builtin_amdgcn_global_load_lds((const unsigned*)((const char*)(gbase) + vo_), (PG8_LAS unsigned*)(lds + (bufoff) + ldsw + _i * 8192), 16, 0, 0); } } while (0)
; #define PG8_LDA(dst, b, h) do { _Pragma("unroll") for (int m = 0; m < 4; ++m) _Pragma("unroll") for (int k = 0; k < 2; ++k) dst[m][k] = *(const PG8_LAS bf16x8*)(lds + PG8_SA(b, h) + aoff + m * 2048 + k * 1024); } while (0)
; #define PG8_WAIT_V(n) asm volatile("s_waitcnt vmcnt(" #n ")" ::: "memory")
; #define PG8_WAIT_L(n) asm volatile("s_waitcnt lgkmcnt(" #n ")" ::: "memory")
; #define PG8_BAR __builtin_amdgcn_s_barrier()
; #define PG8_SCHED __builtin_amdgcn_sched_barrier(0)
; template <class Epi, class Sched, bool ALIGN_EPI = false, bool SP2 = false, bool FP8 = false>
; __device__ __forceinline__ void gemm_phase(PG8_LAS unsigned char* lds, const Gemm g, const Sched& S, const Epi& E) {
;     ...
;             PG8_LDA(At, 1, 1); PG8_STAGE(PG8_SB(1, 0), b3, voffB); PG8_STAGE(PG8_SB(1, 1), b3 + hstep, voffB); PG8_STAGE(PG8_SA(1, 0), a3, voffA);
;             PG8_WAIT_V(8); PG8_WAIT_L(0); PG8_BAR; PG8_MMA(1, 0, At, B0); PG8_MMA(1, 1, At, B1); PG8_BAR; PG8_SCHED;
	v_mov_b32_e32 v178, v198
	ds_read_b128 v[144:147], v202 offset:49152
	ds_read_b128 v[148:151], v202 offset:50176
	ds_read_b128 v[152:155], v202 offset:51200
	ds_read_b128 v[156:159], v202 offset:52224
	ds_read_b128 v[160:163], v202 offset:53248
	ds_read_b128 v[164:167], v202 offset:54272
	ds_read_b128 v[168:171], v202 offset:55296
	ds_read_b128 v[172:175], v202 offset:56320
	s_add_i32 s0, s75, s41
	v_lshl_add_u64 v[8:9], s[56:57], 0, v[178:179]
	v_lshl_add_u64 v[8:9], v[8:9], 0, s[14:15]
	s_mov_b32 m0, s0
	v_mov_b32_e32 v178, v200
	global_load_lds_dwordx4 v[8:9], off
	s_add_i32 m0, s0, 0x2000
	v_lshl_add_u64 v[8:9], s[56:57], 0, v[178:179]
	v_lshl_add_u64 v[8:9], v[8:9], 0, s[14:15]
	s_add_u32 s0, s56, 0x20080
	global_load_lds_dwordx4 v[8:9], off
	s_addc_u32 s1, s57, 0
	v_mov_b32_e32 v8, v198
	s_add_i32 s56, s77, s41
	s_mov_b32 m0, s56
	v_mov_b32_e32 v178, v197
	global_load_lds_dwordx4 v8, s[0:1]
	v_mov_b32_e32 v8, v200
	s_add_i32 m0, s56, 0x2000
	s_nop 0
	global_load_lds_dwordx4 v8, s[0:1]
	s_mov_b32 m0, s66
	v_lshl_add_u64 v[8:9], s[54:55], 0, v[178:179]
	v_lshl_add_u64 v[8:9], v[8:9], 0, s[14:15]
	v_mov_b32_e32 v178, v199
	global_load_lds_dwordx4 v[8:9], off
	s_mov_b32 m0, s67
	v_lshl_add_u64 v[8:9], s[54:55], 0, v[178:179]
	v_lshl_add_u64 v[8:9], v[8:9], 0, s[14:15]
	global_load_lds_dwordx4 v[8:9], off
	s_waitcnt vmcnt(8)
	s_waitcnt lgkmcnt(0)
	s_barrier
	s_setprio 1
	s_waitcnt lgkmcnt(0)
	v_mfma_scale_f32_16x16x128_f8f6f4 v[52:55], v[0:7], v[144:151], v[52:55], v203, v203 op_sel_hi:[0,0,0]
	v_mfma_scale_f32_16x16x128_f8f6f4 v[48:51], v[56:63], v[144:151], v[48:51], v203, v203 op_sel_hi:[0,0,0]
	v_mfma_scale_f32_16x16x128_f8f6f4 v[44:47], v[0:7], v[152:159], v[44:47], v203, v203 op_sel_hi:[0,0,0]
	v_mfma_scale_f32_16x16x128_f8f6f4 v[36:39], v[56:63], v[152:159], v[184:187], v203, v203 op_sel_hi:[0,0,0]
	v_mfma_scale_f32_16x16x128_f8f6f4 v[28:31], v[0:7], v[160:167], v[188:191], v203, v203 op_sel_hi:[0,0,0]
	v_mfma_scale_f32_16x16x128_f8f6f4 v[20:23], v[56:63], v[160:167], v[206:209], v203, v203 op_sel_hi:[0,0,0]
	v_mfma_scale_f32_16x16x128_f8f6f4 v[12:15], v[0:7], v[168:175], v[210:213], v203, v203 op_sel_hi:[0,0,0]
	v_mfma_scale_f32_16x16x128_f8f6f4 v[4:7], v[56:63], v[168:175], v[226:229], v203, v203 op_sel_hi:[0,0,0]
	s_setprio 0
	s_setprio 1
	v_mfma_scale_f32_16x16x128_f8f6f4 v[60:63], v[128:135], v[144:151], v[230:233], v203, v203 op_sel_hi:[0,0,0]
	v_mfma_scale_f32_16x16x128_f8f6f4 v[56:59], v[136:143], v[144:151], v[234:237], v203, v203 op_sel_hi:[0,0,0]
	v_mfma_scale_f32_16x16x128_f8f6f4 v[40:43], v[128:135], v[152:159], v[40:43], v203, v203 op_sel_hi:[0,0,0]
	v_mfma_scale_f32_16x16x128_f8f6f4 v[32:35], v[136:143], v[152:159], v[238:241], v203, v203 op_sel_hi:[0,0,0]
	v_mfma_scale_f32_16x16x128_f8f6f4 v[24:27], v[128:135], v[160:167], v[242:245], v203, v203 op_sel_hi:[0,0,0]
	v_mfma_scale_f32_16x16x128_f8f6f4 v[16:19], v[136:143], v[160:167], v[246:249], v203, v203 op_sel_hi:[0,0,0]
	v_mfma_scale_f32_16x16x128_f8f6f4 v[8:11], v[128:135], v[168:175], v[250:253], v203, v203 op_sel_hi:[0,0,0]
	v_mfma_scale_f32_16x16x128_f8f6f4 v[0:3], v[136:143], v[168:175], v[180:183], v203, v203 op_sel_hi:[0,0,0]
	s_setprio 0
	s_barrier
	s_add_i32 s74, s74, 2
	s_add_u32 s10, s10, 0x100
	s_addc_u32 s11, s11, 0
	s_add_u32 s72, s72, 0x100
	s_addc_u32 s73, s73, 0
	s_cmp_gt_u32 s74, 5
	s_cbranch_scc0 .LBB0_342
	s_and_b64 vcc, exec, s[38:39]
	s_cbranch_vccz .LBB0_345

; #define PG8_STAGE(bufoff, gbase, voff) do { _Pragma("unroll") for (int _i = 0; _i < 2; ++_i) { unsigned vo_ = (voff)[_i]; if constexpr (FP8) asm volatile("" : "+v"(vo_)); \
;         __builtin_amdgcn_global_load_lds((const unsigned*)((const char*)(gbase) + vo_), (PG8_LAS unsigned*)(lds + (bufoff) + ldsw + _i * 8192), 16, 0, 0); } } while (0)
; #define PG8_LDA(dst, b, h) do { _Pragma("unroll") for (int m = 0; m < 4; ++m) _Pragma("unroll") for (int k = 0; k < 2; ++k) dst[m][k] = *(const PG8_LAS bf16x8*)(lds + PG8_SA(b, h) + aoff + m * 2048 + k * 1024); } while (0)
; #define PG8_LDB(dst, b, h) do { _Pragma("unroll") for (int n = 0; n < 2; ++n) _Pragma("unroll") for (int k = 0; k < 2; ++k) dst[n][k] = *(const PG8_LAS bf16x8*)(lds + PG8_SB(b, h) + boff + n * 2048 + k * 1024); } while (0)
; #define PG8_WAIT_V(n) asm volatile("s_waitcnt vmcnt(" #n ")" ::: "memory")
; #define PG8_WAIT_L(n) asm volatile("s_waitcnt lgkmcnt(" #n ")" ::: "memory")
; #define PG8_BAR __builtin_amdgcn_s_barrier()
; #define PG8_SCHED __builtin_amdgcn_sched_barrier(0)
; template <class Epi, class Sched, bool ALIGN_EPI = false, bool SP2 = false, bool FP8 = false>
; __device__ __forceinline__ void gemm_phase(PG8_LAS unsigned char* lds, const Gemm g, const Sched& S, const Epi& E) {
;     ...
;             PG8_LDB(B0, 0, 0); PG8_LDB(B1, 0, 1); PG8_SCHED; PG8_LDA(At, 0, 0); PG8_STAGE(PG8_SA(1, 1), a1 + hstep, voffA);
;             PG8_WAIT_V(8); PG8_WAIT_L(0); PG8_BAR; PG8_MMA(0, 0, At, B0); PG8_MMA(0, 1, At, B1); PG8_BAR; PG8_SCHED;
.Lmy_nobar_P5:
.LBB0_391:
	ds_read_b128 v[146:149], v153
	ds_read_b128 v[158:161], v153 offset:1024
	ds_read_b128 v[162:165], v153 offset:2048
	ds_read_b128 v[166:169], v153 offset:3072
	ds_read_b128 v[170:173], v154
	ds_read_b128 v[174:177], v154 offset:1024
	ds_read_b128 v[178:181], v154 offset:2048
	ds_read_b128 v[182:185], v154 offset:3072
	s_add_u32 s0, s40, 0xfffc0080
	s_addc_u32 s1, s41, -1
	s_cmp_eq_u32 s61, 12
	s_cselect_b32 s45, s15, s1
	s_cselect_b32 s44, s57, s0
	s_cselect_b32 s43, s13, s60
	s_cselect_b32 s42, s58, s59
	v_lshl_add_u64 v[218:219], s[40:41], 0, v[138:139]
	s_add_i32 m0, s39, 0xc000
	ds_read_b128 v[186:189], v155
	ds_read_b128 v[190:193], v155 offset:1024
	ds_read_b128 v[194:197], v155 offset:2048
	ds_read_b128 v[198:201], v155 offset:3072
	ds_read_b128 v[202:205], v155 offset:4096
	ds_read_b128 v[206:209], v155 offset:5120
	ds_read_b128 v[210:213], v155 offset:6144
	ds_read_b128 v[214:217], v155 offset:7168
	global_load_lds_dwordx4 v[218:219], off
	v_lshl_add_u64 v[218:219], s[40:41], 0, v[140:141]
	s_add_i32 m0, s39, 0xe000
	s_nop 0
	global_load_lds_dwordx4 v[218:219], off
	s_cmp_eq_u32 s99, 1
	s_cbranch_scc1 .Lmy_rw_P5_0
	s_waitcnt vmcnt(8)
	s_branch .Lmy_rd_P5_0

; #define PG8_STAGE(bufoff, gbase, voff) do { _Pragma("unroll") for (int _i = 0; _i < 2; ++_i) { unsigned vo_ = (voff)[_i]; if constexpr (FP8) asm volatile("" : "+v"(vo_)); \
;         __builtin_amdgcn_global_load_lds((const unsigned*)((const char*)(gbase) + vo_), (PG8_LAS unsigned*)(lds + (bufoff) + ldsw + _i * 8192), 16, 0, 0); } } while (0)
; #define PG8_LDA(dst, b, h) do { _Pragma("unroll") for (int m = 0; m < 4; ++m) _Pragma("unroll") for (int k = 0; k < 2; ++k) dst[m][k] = *(const PG8_LAS bf16x8*)(lds + PG8_SA(b, h) + aoff + m * 2048 + k * 1024); } while (0)
; #define PG8_WAIT_V(n) asm volatile("s_waitcnt vmcnt(" #n ")" ::: "memory")
; #define PG8_WAIT_L(n) asm volatile("s_waitcnt lgkmcnt(" #n ")" ::: "memory")
; #define PG8_BAR __builtin_amdgcn_s_barrier()
; #define PG8_SCHED __builtin_amdgcn_sched_barrier(0)
; template <class Epi, class Sched, bool ALIGN_EPI = false, bool SP2 = false, bool FP8 = false>
; __device__ __forceinline__ void gemm_phase(PG8_LAS unsigned char* lds, const Gemm g, const Sched& S, const Epi& E) {
;     ...
;             PG8_WAIT_V(8); PG8_WAIT_L(0); PG8_BAR; PG8_MMA(0, 0, At, B0); PG8_MMA(0, 1, At, B1); PG8_BAR; PG8_SCHED;
;             PG8_LDA(At, 0, 1); PG8_STAGE(PG8_SB(0, 0), b2, voffB); PG8_STAGE(PG8_SB(0, 1), b2 + hstep, voffB); PG8_STAGE(PG8_SA(0, 0), a2, voffA);
;             PG8_WAIT_V(8); PG8_WAIT_L(0); PG8_BAR; PG8_MMA(1, 0, At, B0); PG8_MMA(1, 1, At, B1); PG8_BAR; PG8_SCHED;
.Lmy_rd_P5_0:
	s_waitcnt lgkmcnt(0)
	s_barrier
	s_setprio 1
	s_waitcnt lgkmcnt(0)
	v_mfma_f32_16x16x32_bf16 v[124:127], v[146:149], v[186:189], v[124:127]
	v_mfma_f32_16x16x32_bf16 v[120:123], v[162:165], v[186:189], v[120:123]
	v_mfma_f32_16x16x32_bf16 v[108:111], v[146:149], v[194:197], v[108:111]
	v_mfma_f32_16x16x32_bf16 v[104:107], v[162:165], v[194:197], v[104:107]
	v_mfma_f32_16x16x32_bf16 v[92:95], v[146:149], v[202:205], v[92:95]
	v_mfma_f32_16x16x32_bf16 v[88:91], v[162:165], v[202:205], v[88:91]
	v_mfma_f32_16x16x32_bf16 v[76:79], v[146:149], v[210:213], v[76:79]
	v_mfma_f32_16x16x32_bf16 v[72:75], v[162:165], v[210:213], v[72:75]
	v_mfma_f32_16x16x32_bf16 v[124:127], v[158:161], v[190:193], v[124:127]
	v_mfma_f32_16x16x32_bf16 v[120:123], v[166:169], v[190:193], v[120:123]
	v_mfma_f32_16x16x32_bf16 v[108:111], v[158:161], v[198:201], v[108:111]
	v_mfma_f32_16x16x32_bf16 v[104:107], v[166:169], v[198:201], v[104:107]
	v_mfma_f32_16x16x32_bf16 v[92:95], v[158:161], v[206:209], v[92:95]
	v_mfma_f32_16x16x32_bf16 v[88:91], v[166:169], v[206:209], v[88:91]
	v_mfma_f32_16x16x32_bf16 v[76:79], v[158:161], v[214:217], v[76:79]
	v_mfma_f32_16x16x32_bf16 v[72:75], v[166:169], v[214:217], v[72:75]
	s_setprio 0
	s_setprio 1
	v_mfma_f32_16x16x32_bf16 v[116:119], v[170:173], v[186:189], v[116:119]
	v_mfma_f32_16x16x32_bf16 v[112:115], v[178:181], v[186:189], v[112:115]
	v_mfma_f32_16x16x32_bf16 v[100:103], v[170:173], v[194:197], v[100:103]
	v_mfma_f32_16x16x32_bf16 v[96:99], v[178:181], v[194:197], v[96:99]
	v_mfma_f32_16x16x32_bf16 v[84:87], v[170:173], v[202:205], v[84:87]
	v_mfma_f32_16x16x32_bf16 v[80:83], v[178:181], v[202:205], v[80:83]
	v_mfma_f32_16x16x32_bf16 v[68:71], v[170:173], v[210:213], v[68:71]
	v_mfma_f32_16x16x32_bf16 v[64:67], v[178:181], v[210:213], v[64:67]
	v_mfma_f32_16x16x32_bf16 v[116:119], v[174:177], v[190:193], v[116:119]
	v_mfma_f32_16x16x32_bf16 v[112:115], v[182:185], v[190:193], v[112:115]
	v_mfma_f32_16x16x32_bf16 v[100:103], v[174:177], v[198:201], v[100:103]
	v_mfma_f32_16x16x32_bf16 v[96:99], v[182:185], v[198:201], v[96:99]
	v_mfma_f32_16x16x32_bf16 v[84:87], v[174:177], v[206:209], v[84:87]
	v_mfma_f32_16x16x32_bf16 v[80:83], v[182:185], v[206:209], v[80:83]
	v_mfma_f32_16x16x32_bf16 v[68:71], v[174:177], v[214:217], v[68:71]
	v_mfma_f32_16x16x32_bf16 v[64:67], v[182:185], v[214:217], v[64:67]
	s_setprio 0
	s_barrier
	s_add_i32 s0, s54, s46
	v_lshl_add_u64 v[218:219], s[42:43], 0, v[132:133]
	s_mov_b32 m0, s0
	ds_read_b128 v[186:189], v155 offset:16384
	ds_read_b128 v[190:193], v155 offset:17408
	ds_read_b128 v[194:197], v155 offset:18432
	ds_read_b128 v[198:201], v155 offset:19456
	ds_read_b128 v[202:205], v155 offset:20480
	ds_read_b128 v[206:209], v155 offset:21504
	ds_read_b128 v[210:213], v155 offset:22528
	ds_read_b128 v[214:217], v155 offset:23552
	global_load_lds_dwordx4 v[218:219], off
	s_add_i32 m0, s0, 0x2000
	s_add_u32 s0, s42, 0x40000
	v_lshl_add_u64 v[220:221], s[42:43], 0, v[128:129]
	s_addc_u32 s1, s43, 0
	s_add_i32 s62, s55, s46
	global_load_lds_dwordx4 v[220:221], off
	v_lshl_add_u64 v[222:223], s[0:1], 0, v[132:133]
	s_mov_b32 m0, s62
	v_lshl_add_u64 v[224:225], s[44:45], 0, v[130:131]
	global_load_lds_dwordx4 v[222:223], off
	v_lshl_add_u64 v[222:223], s[0:1], 0, v[128:129]
	s_add_i32 m0, s62, 0x2000
	s_nop 0
	global_load_lds_dwordx4 v[222:223], off
	v_lshl_add_u64 v[222:223], s[44:45], 0, v[134:135]
	s_mov_b32 m0, s39
	s_nop 0
	global_load_lds_dwordx4 v[222:223], off
	s_mov_b32 m0, s48
	s_nop 0
	global_load_lds_dwordx4 v[224:225], off
	s_cmp_eq_u32 s99, 1
	s_cbranch_scc1 .Lmy_rw_P5_1
	s_waitcnt vmcnt(8)
	s_branch .Lmy_rd_P5_1

; #define PG8_STAGE(bufoff, gbase, voff) do { _Pragma("unroll") for (int _i = 0; _i < 2; ++_i) { unsigned vo_ = (voff)[_i]; if constexpr (FP8) asm volatile("" : "+v"(vo_)); \
;         __builtin_amdgcn_global_load_lds((const unsigned*)((const char*)(gbase) + vo_), (PG8_LAS unsigned*)(lds + (bufoff) + ldsw + _i * 8192), 16, 0, 0); } } while (0)
; #define PG8_LDA(dst, b, h) do { _Pragma("unroll") for (int m = 0; m < 4; ++m) _Pragma("unroll") for (int k = 0; k < 2; ++k) dst[m][k] = *(const PG8_LAS bf16x8*)(lds + PG8_SA(b, h) + aoff + m * 2048 + k * 1024); } while (0)
; #define PG8_LDB(dst, b, h) do { _Pragma("unroll") for (int n = 0; n < 2; ++n) _Pragma("unroll") for (int k = 0; k < 2; ++k) dst[n][k] = *(const PG8_LAS bf16x8*)(lds + PG8_SB(b, h) + boff + n * 2048 + k * 1024); } while (0)
; #define PG8_WAIT_V(n) asm volatile("s_waitcnt vmcnt(" #n ")" ::: "memory")
; #define PG8_WAIT_L(n) asm volatile("s_waitcnt lgkmcnt(" #n ")" ::: "memory")
; #define PG8_BAR __builtin_amdgcn_s_barrier()
; #define PG8_SCHED __builtin_amdgcn_sched_barrier(0)
; template <class Epi, class Sched, bool ALIGN_EPI = false, bool SP2 = false, bool FP8 = false>
; __device__ __forceinline__ void gemm_phase(PG8_LAS unsigned char* lds, const Gemm g, const Sched& S, const Epi& E) {
;     ...
;             PG8_WAIT_V(8); PG8_WAIT_L(0); PG8_BAR; PG8_MMA(1, 0, At, B0); PG8_MMA(1, 1, At, B1); PG8_BAR; PG8_SCHED;
;             PG8_LDB(B0, 1, 0); PG8_LDB(B1, 1, 1); PG8_SCHED; PG8_LDA(At, 1, 0); PG8_STAGE(PG8_SA(0, 1), a2 + hstep, voffA);
;             PG8_WAIT_V(8); PG8_WAIT_L(0); PG8_BAR; PG8_MMA(0, 0, At, B0); PG8_MMA(0, 1, At, B1); PG8_BAR; PG8_SCHED;
;             PG8_LDA(At, 1, 1); PG8_STAGE(PG8_SB(1, 0), b3, voffB); PG8_STAGE(PG8_SB(1, 1), b3 + hstep, voffB); PG8_STAGE(PG8_SA(1, 0), a3, voffA);
.Lmy_rd_P5_1:
	s_mov_b32 s99, 0
	s_waitcnt lgkmcnt(0)
	s_barrier
	s_setprio 1
	s_waitcnt lgkmcnt(0)
	v_mfma_f32_16x16x32_bf16 v[60:63], v[146:149], v[186:189], v[60:63]
	v_mfma_f32_16x16x32_bf16 v[56:59], v[162:165], v[186:189], v[56:59]
	v_mfma_f32_16x16x32_bf16 v[44:47], v[146:149], v[194:197], v[44:47]
	v_mfma_f32_16x16x32_bf16 v[40:43], v[162:165], v[194:197], v[40:43]
	v_mfma_f32_16x16x32_bf16 v[28:31], v[146:149], v[202:205], v[28:31]
	v_mfma_f32_16x16x32_bf16 v[24:27], v[162:165], v[202:205], v[24:27]
	v_mfma_f32_16x16x32_bf16 v[12:15], v[146:149], v[210:213], v[12:15]
	v_mfma_f32_16x16x32_bf16 v[8:11], v[162:165], v[210:213], v[8:11]
	v_mfma_f32_16x16x32_bf16 v[60:63], v[158:161], v[190:193], v[60:63]
	v_mfma_f32_16x16x32_bf16 v[56:59], v[166:169], v[190:193], v[56:59]
	v_mfma_f32_16x16x32_bf16 v[44:47], v[158:161], v[198:201], v[44:47]
	v_mfma_f32_16x16x32_bf16 v[40:43], v[166:169], v[198:201], v[40:43]
	v_mfma_f32_16x16x32_bf16 v[28:31], v[158:161], v[206:209], v[28:31]
	v_mfma_f32_16x16x32_bf16 v[24:27], v[166:169], v[206:209], v[24:27]
	v_mfma_f32_16x16x32_bf16 v[12:15], v[158:161], v[214:217], v[12:15]
	v_mfma_f32_16x16x32_bf16 v[8:11], v[166:169], v[214:217], v[8:11]
	s_setprio 0
	s_setprio 1
	v_mfma_f32_16x16x32_bf16 v[52:55], v[170:173], v[186:189], v[52:55]
	v_mfma_f32_16x16x32_bf16 v[48:51], v[178:181], v[186:189], v[48:51]
	v_mfma_f32_16x16x32_bf16 v[36:39], v[170:173], v[194:197], v[36:39]
	v_mfma_f32_16x16x32_bf16 v[32:35], v[178:181], v[194:197], v[32:35]
	v_mfma_f32_16x16x32_bf16 v[20:23], v[170:173], v[202:205], v[20:23]
	v_mfma_f32_16x16x32_bf16 v[16:19], v[178:181], v[202:205], v[16:19]
	v_mfma_f32_16x16x32_bf16 v[4:7], v[170:173], v[210:213], v[4:7]
	v_mfma_f32_16x16x32_bf16 v[0:3], v[178:181], v[210:213], v[0:3]
	v_mfma_f32_16x16x32_bf16 v[52:55], v[174:177], v[190:193], v[52:55]
	v_mfma_f32_16x16x32_bf16 v[48:51], v[182:185], v[190:193], v[48:51]
	v_mfma_f32_16x16x32_bf16 v[36:39], v[174:177], v[198:201], v[36:39]
	v_mfma_f32_16x16x32_bf16 v[32:35], v[182:185], v[198:201], v[32:35]
	v_mfma_f32_16x16x32_bf16 v[20:23], v[174:177], v[206:209], v[20:23]
	v_mfma_f32_16x16x32_bf16 v[16:19], v[182:185], v[206:209], v[16:19]
	v_mfma_f32_16x16x32_bf16 v[4:7], v[174:177], v[214:217], v[4:7]
	v_mfma_f32_16x16x32_bf16 v[0:3], v[182:185], v[214:217], v[0:3]
	s_setprio 0
	s_barrier
	s_add_i32 s62, 0, 0x18000
	s_add_i32 s63, 0, 0x1c000
	v_add_u32_e32 v166, s62, v151
	v_add_u32_e32 v182, s63, v151
	ds_read_b128 v[146:149], v166
	ds_read_b128 v[158:161], v166 offset:1024
	ds_read_b128 v[162:165], v166 offset:2048
	ds_read_b128 v[166:169], v166 offset:3072
	ds_read_b128 v[170:173], v182
	ds_read_b128 v[174:177], v182 offset:1024
	ds_read_b128 v[178:181], v182 offset:2048
	ds_read_b128 v[182:185], v182 offset:3072
	s_add_u32 s0, s44, 0x40000
	s_addc_u32 s1, s45, 0
	s_mov_b32 m0, s49
	v_lshl_add_u64 v[226:227], s[0:1], 0, v[134:135]
	ds_read_b128 v[186:189], v155 offset:32768
	ds_read_b128 v[190:193], v155 offset:33792
	ds_read_b128 v[194:197], v155 offset:34816
	ds_read_b128 v[198:201], v155 offset:35840
	ds_read_b128 v[202:205], v155 offset:36864
	ds_read_b128 v[206:209], v155 offset:37888
	ds_read_b128 v[210:213], v155 offset:38912
	ds_read_b128 v[214:217], v155 offset:39936
	global_load_lds_dwordx4 v[226:227], off
	v_lshl_add_u64 v[226:227], s[0:1], 0, v[130:131]
	s_mov_b32 m0, s50
	s_nop 0
	global_load_lds_dwordx4 v[226:227], off
	s_waitcnt vmcnt(8)
	s_waitcnt lgkmcnt(0)
	s_barrier
	s_setprio 1
	s_waitcnt lgkmcnt(0)
	v_mfma_f32_16x16x32_bf16 v[124:127], v[146:149], v[186:189], v[124:127]
	v_mfma_f32_16x16x32_bf16 v[120:123], v[162:165], v[186:189], v[120:123]
	v_mfma_f32_16x16x32_bf16 v[108:111], v[146:149], v[194:197], v[108:111]
	v_mfma_f32_16x16x32_bf16 v[104:107], v[162:165], v[194:197], v[104:107]
	v_mfma_f32_16x16x32_bf16 v[92:95], v[146:149], v[202:205], v[92:95]
	v_mfma_f32_16x16x32_bf16 v[88:91], v[162:165], v[202:205], v[88:91]
	v_mfma_f32_16x16x32_bf16 v[76:79], v[146:149], v[210:213], v[76:79]
	v_mfma_f32_16x16x32_bf16 v[72:75], v[162:165], v[210:213], v[72:75]
	v_mfma_f32_16x16x32_bf16 v[124:127], v[158:161], v[190:193], v[124:127]
	v_mfma_f32_16x16x32_bf16 v[120:123], v[166:169], v[190:193], v[120:123]
	v_mfma_f32_16x16x32_bf16 v[108:111], v[158:161], v[198:201], v[108:111]
	v_mfma_f32_16x16x32_bf16 v[104:107], v[166:169], v[198:201], v[104:107]
	v_mfma_f32_16x16x32_bf16 v[92:95], v[158:161], v[206:209], v[92:95]
	v_mfma_f32_16x16x32_bf16 v[88:91], v[166:169], v[206:209], v[88:91]
	v_mfma_f32_16x16x32_bf16 v[76:79], v[158:161], v[214:217], v[76:79]
	v_mfma_f32_16x16x32_bf16 v[72:75], v[166:169], v[214:217], v[72:75]
	s_setprio 0
	s_setprio 1
	v_mfma_f32_16x16x32_bf16 v[116:119], v[170:173], v[186:189], v[116:119]
	v_mfma_f32_16x16x32_bf16 v[112:115], v[178:181], v[186:189], v[112:115]
	v_mfma_f32_16x16x32_bf16 v[100:103], v[170:173], v[194:197], v[100:103]
	v_mfma_f32_16x16x32_bf16 v[96:99], v[178:181], v[194:197], v[96:99]
	v_mfma_f32_16x16x32_bf16 v[84:87], v[170:173], v[202:205], v[84:87]
	v_mfma_f32_16x16x32_bf16 v[80:83], v[178:181], v[202:205], v[80:83]
	v_mfma_f32_16x16x32_bf16 v[68:71], v[170:173], v[210:213], v[68:71]
	v_mfma_f32_16x16x32_bf16 v[64:67], v[178:181], v[210:213], v[64:67]
	v_mfma_f32_16x16x32_bf16 v[116:119], v[174:177], v[190:193], v[116:119]
	v_mfma_f32_16x16x32_bf16 v[112:115], v[182:185], v[190:193], v[112:115]
	v_mfma_f32_16x16x32_bf16 v[100:103], v[174:177], v[198:201], v[100:103]
	v_mfma_f32_16x16x32_bf16 v[96:99], v[182:185], v[198:201], v[96:99]
	v_mfma_f32_16x16x32_bf16 v[84:87], v[174:177], v[206:209], v[84:87]
	v_mfma_f32_16x16x32_bf16 v[80:83], v[182:185], v[206:209], v[80:83]
	v_mfma_f32_16x16x32_bf16 v[68:71], v[174:177], v[214:217], v[68:71]
	v_mfma_f32_16x16x32_bf16 v[64:67], v[182:185], v[214:217], v[64:67]
	s_setprio 0
	s_barrier
; #define PG8_STAGE(bufoff, gbase, voff) do { _Pragma("unroll") for (int _i = 0; _i < 2; ++_i) { unsigned vo_ = (voff)[_i]; if constexpr (FP8) asm volatile("" : "+v"(vo_)); \
;         __builtin_amdgcn_global_load_lds((const unsigned*)((const char*)(gbase) + vo_), (PG8_LAS unsigned*)(lds + (bufoff) + ldsw + _i * 8192), 16, 0, 0); } } while (0)
; #define PG8_LDA(dst, b, h) do { _Pragma("unroll") for (int m = 0; m < 4; ++m) _Pragma("unroll") for (int k = 0; k < 2; ++k) dst[m][k] = *(const PG8_LAS bf16x8*)(lds + PG8_SA(b, h) + aoff + m * 2048 + k * 1024); } while (0)
; #define PG8_WAIT_V(n) asm volatile("s_waitcnt vmcnt(" #n ")" ::: "memory")
; #define PG8_WAIT_L(n) asm volatile("s_waitcnt lgkmcnt(" #n ")" ::: "memory")
; #define PG8_BAR __builtin_amdgcn_s_barrier()
; #define PG8_SCHED __builtin_amdgcn_sched_barrier(0)
; template <class Epi, class Sched, bool ALIGN_EPI = false, bool SP2 = false, bool FP8 = false>
; __device__ __forceinline__ void gemm_phase(PG8_LAS unsigned char* lds, const Gemm g, const Sched& S, const Epi& E) {
;     ...
;             PG8_LDA(At, 1, 1); PG8_STAGE(PG8_SB(1, 0), b3, voffB); PG8_STAGE(PG8_SB(1, 1), b3 + hstep, voffB); PG8_STAGE(PG8_SA(1, 0), a3, voffA);
;             PG8_WAIT_V(8); PG8_WAIT_L(0); PG8_BAR; PG8_MMA(1, 0, At, B0); PG8_MMA(1, 1, At, B1); PG8_BAR; PG8_SCHED;
	s_add_i32 s0, s62, s46
	v_lshl_add_u64 v[218:219], v[218:219], 0, s[8:9]
	s_mov_b32 m0, s0
	ds_read_b128 v[186:189], v155 offset:49152
	ds_read_b128 v[190:193], v155 offset:50176
	ds_read_b128 v[194:197], v155 offset:51200
	ds_read_b128 v[198:201], v155 offset:52224
	ds_read_b128 v[202:205], v155 offset:53248
	ds_read_b128 v[206:209], v155 offset:54272
	ds_read_b128 v[210:213], v155 offset:55296
	ds_read_b128 v[214:217], v155 offset:56320
	global_load_lds_dwordx4 v[218:219], off
	s_add_i32 m0, s0, 0x2000
	s_add_u32 s0, s42, 0x40080
	v_lshl_add_u64 v[218:219], v[220:221], 0, s[8:9]
	s_addc_u32 s1, s43, 0
	s_add_i32 s42, s63, s46
	global_load_lds_dwordx4 v[218:219], off
	v_lshl_add_u64 v[218:219], s[0:1], 0, v[132:133]
	s_mov_b32 m0, s42
	s_nop 0
	global_load_lds_dwordx4 v[218:219], off
	v_lshl_add_u64 v[218:219], s[0:1], 0, v[128:129]
	s_add_i32 m0, s42, 0x2000
	s_nop 0
	global_load_lds_dwordx4 v[218:219], off
	v_lshl_add_u64 v[218:219], v[222:223], 0, s[8:9]
	s_mov_b32 m0, s52
	s_nop 0
	global_load_lds_dwordx4 v[218:219], off
	v_lshl_add_u64 v[218:219], v[224:225], 0, s[8:9]
	s_mov_b32 m0, s53
	s_nop 0
	global_load_lds_dwordx4 v[218:219], off
	s_waitcnt vmcnt(8)
	s_waitcnt lgkmcnt(0)
	s_barrier
	s_setprio 1
	s_waitcnt lgkmcnt(0)
	v_mfma_f32_16x16x32_bf16 v[60:63], v[146:149], v[186:189], v[60:63]
	v_mfma_f32_16x16x32_bf16 v[56:59], v[162:165], v[186:189], v[56:59]
	v_mfma_f32_16x16x32_bf16 v[44:47], v[146:149], v[194:197], v[44:47]
	v_mfma_f32_16x16x32_bf16 v[40:43], v[162:165], v[194:197], v[40:43]
	v_mfma_f32_16x16x32_bf16 v[28:31], v[146:149], v[202:205], v[28:31]
	v_mfma_f32_16x16x32_bf16 v[24:27], v[162:165], v[202:205], v[24:27]
	v_mfma_f32_16x16x32_bf16 v[12:15], v[146:149], v[210:213], v[12:15]
	v_mfma_f32_16x16x32_bf16 v[8:11], v[162:165], v[210:213], v[8:11]
	v_mfma_f32_16x16x32_bf16 v[60:63], v[158:161], v[190:193], v[60:63]
	v_mfma_f32_16x16x32_bf16 v[56:59], v[166:169], v[190:193], v[56:59]
	v_mfma_f32_16x16x32_bf16 v[44:47], v[158:161], v[198:201], v[44:47]
	v_mfma_f32_16x16x32_bf16 v[40:43], v[166:169], v[198:201], v[40:43]
	v_mfma_f32_16x16x32_bf16 v[28:31], v[158:161], v[206:209], v[28:31]
	v_mfma_f32_16x16x32_bf16 v[24:27], v[166:169], v[206:209], v[24:27]
	v_mfma_f32_16x16x32_bf16 v[12:15], v[158:161], v[214:217], v[12:15]
	v_mfma_f32_16x16x32_bf16 v[8:11], v[166:169], v[214:217], v[8:11]
	s_setprio 0
	s_setprio 1
	v_mfma_f32_16x16x32_bf16 v[52:55], v[170:173], v[186:189], v[52:55]
	v_mfma_f32_16x16x32_bf16 v[48:51], v[178:181], v[186:189], v[48:51]
	v_mfma_f32_16x16x32_bf16 v[36:39], v[170:173], v[194:197], v[36:39]
	v_mfma_f32_16x16x32_bf16 v[32:35], v[178:181], v[194:197], v[32:35]
	v_mfma_f32_16x16x32_bf16 v[20:23], v[170:173], v[202:205], v[20:23]
	v_mfma_f32_16x16x32_bf16 v[16:19], v[178:181], v[202:205], v[16:19]
	v_mfma_f32_16x16x32_bf16 v[4:7], v[170:173], v[210:213], v[4:7]
	v_mfma_f32_16x16x32_bf16 v[0:3], v[178:181], v[210:213], v[0:3]
	v_mfma_f32_16x16x32_bf16 v[52:55], v[174:177], v[190:193], v[52:55]
	v_mfma_f32_16x16x32_bf16 v[48:51], v[182:185], v[190:193], v[48:51]
	v_mfma_f32_16x16x32_bf16 v[36:39], v[174:177], v[198:201], v[36:39]
	v_mfma_f32_16x16x32_bf16 v[32:35], v[182:185], v[198:201], v[32:35]
	v_mfma_f32_16x16x32_bf16 v[20:23], v[174:177], v[206:209], v[20:23]
	v_mfma_f32_16x16x32_bf16 v[16:19], v[182:185], v[206:209], v[16:19]
	v_mfma_f32_16x16x32_bf16 v[4:7], v[174:177], v[214:217], v[4:7]
	v_mfma_f32_16x16x32_bf16 v[0:3], v[182:185], v[214:217], v[0:3]
	s_setprio 0
	s_barrier
	s_add_i32 s61, s61, 2
	s_add_u32 s40, s40, 0x100
	s_addc_u32 s41, s41, 0
	s_add_u32 s59, s59, 0x100
	s_addc_u32 s60, s60, 0
	s_cmp_gt_u32 s61, 13
	s_cbranch_scc0 .LBB0_391
	s_and_b64 vcc, exec, s[10:11]
	s_cbranch_vccz .LBB0_394
	s_barrier

; #define PG8_STAGE(bufoff, gbase, voff) do { _Pragma("unroll") for (int _i = 0; _i < 2; ++_i) { unsigned vo_ = (voff)[_i]; if constexpr (FP8) asm volatile("" : "+v"(vo_)); \
;         __builtin_amdgcn_global_load_lds((const unsigned*)((const char*)(gbase) + vo_), (PG8_LAS unsigned*)(lds + (bufoff) + ldsw + _i * 8192), 16, 0, 0); } } while (0)
; #define PG8_LDA(dst, b, h) do { _Pragma("unroll") for (int m = 0; m < 4; ++m) _Pragma("unroll") for (int k = 0; k < 2; ++k) dst[m][k] = *(const PG8_LAS bf16x8*)(lds + PG8_SA(b, h) + aoff + m * 2048 + k * 1024); } while (0)
; #define PG8_LDB(dst, b, h) do { _Pragma("unroll") for (int n = 0; n < 2; ++n) _Pragma("unroll") for (int k = 0; k < 2; ++k) dst[n][k] = *(const PG8_LAS bf16x8*)(lds + PG8_SB(b, h) + boff + n * 2048 + k * 1024); } while (0)
; #define PG8_WAIT_V(n) asm volatile("s_waitcnt vmcnt(" #n ")" ::: "memory")
; #define PG8_WAIT_L(n) asm volatile("s_waitcnt lgkmcnt(" #n ")" ::: "memory")
; #define PG8_BAR __builtin_amdgcn_s_barrier()
; #define PG8_SCHED __builtin_amdgcn_sched_barrier(0)
; template <class Epi, class Sched, bool ALIGN_EPI = false, bool SP2 = false, bool FP8 = false>
; __device__ __forceinline__ void gemm_phase(PG8_LAS unsigned char* lds, const Gemm g, const Sched& S, const Epi& E) {
;     ...
;             PG8_LDB(B0, 0, 0); PG8_LDB(B1, 0, 1); PG8_SCHED; PG8_LDA(At, 0, 0); PG8_STAGE(PG8_SA(1, 1), a1 + hstep, voffA);
;             PG8_WAIT_V(8); PG8_WAIT_L(0); PG8_BAR; PG8_MMA(0, 0, At, B0); PG8_MMA(0, 1, At, B1); PG8_BAR; PG8_SCHED;
;             PG8_LDA(At, 0, 1); PG8_STAGE(PG8_SB(0, 0), b2, voffB); PG8_STAGE(PG8_SB(0, 1), b2 + hstep, voffB); PG8_STAGE(PG8_SA(0, 0), a2, voffA);
;             PG8_WAIT_V(8); PG8_WAIT_L(0); PG8_BAR; PG8_MMA(1, 0, At, B0); PG8_MMA(1, 1, At, B1); PG8_BAR; PG8_SCHED;
.Lmy_nobar_P6:
.LBB0_427:
	ds_read_b128 v[128:131], v201
	ds_read_b128 v[132:135], v201 offset:1024
	ds_read_b128 v[136:139], v201 offset:2048
	ds_read_b128 v[140:143], v201 offset:3072
	ds_read_b128 v[144:147], v202
	ds_read_b128 v[148:151], v202 offset:1024
	ds_read_b128 v[170:173], v202 offset:2048
	ds_read_b128 v[174:177], v202 offset:3072
	s_add_u32 s42, s40, 0xfff00080
	s_addc_u32 s43, s41, -1
	s_cmp_eq_u32 s63, 60
	s_cselect_b32 s45, s31, s43
	s_cselect_b32 s44, s39, s42
	s_cselect_b32 s43, s23, s62
	s_cselect_b32 s42, s60, s61
	v_lshl_add_u64 v[218:219], s[40:41], 0, v[162:163]
	s_add_i32 m0, s47, 0xc000
	ds_read_b128 v[178:181], v203
	ds_read_b128 v[182:185], v203 offset:1024
	ds_read_b128 v[186:189], v203 offset:2048
	ds_read_b128 v[190:193], v203 offset:3072
	ds_read_b128 v[194:197], v203 offset:4096
	ds_read_b128 v[206:209], v203 offset:5120
	ds_read_b128 v[210:213], v203 offset:6144
	ds_read_b128 v[214:217], v203 offset:7168
	global_load_lds_dwordx4 v[218:219], off
	v_lshl_add_u64 v[218:219], s[40:41], 0, v[164:165]
	s_add_i32 m0, s47, 0xe000
	s_nop 0
	global_load_lds_dwordx4 v[218:219], off
	s_cmp_eq_u32 s99, 1
	s_cbranch_scc1 .Lmy_rw_P6_0
	s_waitcnt vmcnt(8)
	s_branch .Lmy_rd_P6_0
.Lmy_rw_P6_0:
	s_waitcnt vmcnt(40)
.Lmy_rd_P6_0:
	s_waitcnt lgkmcnt(0)
	s_barrier
	s_setprio 1
	s_waitcnt lgkmcnt(0)
	v_mfma_f32_16x16x32_bf16 v[124:127], v[128:131], v[178:181], v[124:127]
	v_mfma_f32_16x16x32_bf16 v[120:123], v[136:139], v[178:181], v[120:123]
	v_mfma_f32_16x16x32_bf16 v[108:111], v[128:131], v[186:189], v[108:111]
	v_mfma_f32_16x16x32_bf16 v[104:107], v[136:139], v[186:189], v[104:107]
	v_mfma_f32_16x16x32_bf16 v[92:95], v[128:131], v[194:197], v[92:95]
	v_mfma_f32_16x16x32_bf16 v[88:91], v[136:139], v[194:197], v[88:91]
	v_mfma_f32_16x16x32_bf16 v[76:79], v[128:131], v[210:213], v[76:79]
	v_mfma_f32_16x16x32_bf16 v[72:75], v[136:139], v[210:213], v[72:75]
	v_mfma_f32_16x16x32_bf16 v[124:127], v[132:135], v[182:185], v[124:127]
	v_mfma_f32_16x16x32_bf16 v[120:123], v[140:143], v[182:185], v[120:123]
	v_mfma_f32_16x16x32_bf16 v[108:111], v[132:135], v[190:193], v[108:111]
	v_mfma_f32_16x16x32_bf16 v[104:107], v[140:143], v[190:193], v[104:107]
	v_mfma_f32_16x16x32_bf16 v[92:95], v[132:135], v[206:209], v[92:95]
	v_mfma_f32_16x16x32_bf16 v[88:91], v[140:143], v[206:209], v[88:91]
	v_mfma_f32_16x16x32_bf16 v[76:79], v[132:135], v[214:217], v[76:79]
	v_mfma_f32_16x16x32_bf16 v[72:75], v[140:143], v[214:217], v[72:75]
	s_setprio 0
	s_setprio 1
	v_mfma_f32_16x16x32_bf16 v[116:119], v[144:147], v[178:181], v[116:119]
	v_mfma_f32_16x16x32_bf16 v[112:115], v[170:173], v[178:181], v[112:115]
	v_mfma_f32_16x16x32_bf16 v[100:103], v[144:147], v[186:189], v[100:103]
	v_mfma_f32_16x16x32_bf16 v[96:99], v[170:173], v[186:189], v[96:99]
	v_mfma_f32_16x16x32_bf16 v[84:87], v[144:147], v[194:197], v[84:87]
	v_mfma_f32_16x16x32_bf16 v[80:83], v[170:173], v[194:197], v[80:83]
	v_mfma_f32_16x16x32_bf16 v[68:71], v[144:147], v[210:213], v[68:71]
	v_mfma_f32_16x16x32_bf16 v[64:67], v[170:173], v[210:213], v[64:67]
	v_mfma_f32_16x16x32_bf16 v[116:119], v[148:151], v[182:185], v[116:119]
	v_mfma_f32_16x16x32_bf16 v[112:115], v[174:177], v[182:185], v[112:115]
	v_mfma_f32_16x16x32_bf16 v[100:103], v[148:151], v[190:193], v[100:103]
	v_mfma_f32_16x16x32_bf16 v[96:99], v[174:177], v[190:193], v[96:99]
	v_mfma_f32_16x16x32_bf16 v[84:87], v[148:151], v[206:209], v[84:87]
	v_mfma_f32_16x16x32_bf16 v[80:83], v[174:177], v[206:209], v[80:83]
	v_mfma_f32_16x16x32_bf16 v[68:71], v[148:151], v[214:217], v[68:71]
	v_mfma_f32_16x16x32_bf16 v[64:67], v[174:177], v[214:217], v[64:67]
	s_setprio 0
	s_barrier
	s_add_i32 s64, s57, s46
	v_lshl_add_u64 v[218:219], s[42:43], 0, v[154:155]
	s_mov_b32 m0, s64
	ds_read_b128 v[178:181], v203 offset:16384
	ds_read_b128 v[182:185], v203 offset:17408
	ds_read_b128 v[186:189], v203 offset:18432
	ds_read_b128 v[190:193], v203 offset:19456
	ds_read_b128 v[194:197], v203 offset:20480
	ds_read_b128 v[206:209], v203 offset:21504
	ds_read_b128 v[210:213], v203 offset:22528
	ds_read_b128 v[214:217], v203 offset:23552
	global_load_lds_dwordx4 v[218:219], off
	s_add_i32 m0, s64, 0x2000
	s_add_u32 s64, s42, 0x100000
	v_lshl_add_u64 v[220:221], s[42:43], 0, v[158:159]
	s_addc_u32 s65, s43, 0
	s_add_i32 s66, s58, s46
	global_load_lds_dwordx4 v[220:221], off
	v_lshl_add_u64 v[222:223], s[64:65], 0, v[154:155]
	s_mov_b32 m0, s66
	v_lshl_add_u64 v[224:225], s[44:45], 0, v[156:157]
	global_load_lds_dwordx4 v[222:223], off
	v_lshl_add_u64 v[222:223], s[64:65], 0, v[158:159]
	s_add_i32 m0, s66, 0x2000
	s_nop 0
	global_load_lds_dwordx4 v[222:223], off
	v_lshl_add_u64 v[222:223], s[44:45], 0, v[152:153]
	s_mov_b32 m0, s47
	s_nop 0
	global_load_lds_dwordx4 v[222:223], off
	s_mov_b32 m0, s48
	s_nop 0
	global_load_lds_dwordx4 v[224:225], off
	s_cmp_eq_u32 s99, 1
	s_cbranch_scc1 .Lmy_rw_P6_1
	s_waitcnt vmcnt(8)
	s_branch .Lmy_rd_P6_1

; #define PG8_STAGE(bufoff, gbase, voff) do { _Pragma("unroll") for (int _i = 0; _i < 2; ++_i) { unsigned vo_ = (voff)[_i]; if constexpr (FP8) asm volatile("" : "+v"(vo_)); \
;         __builtin_amdgcn_global_load_lds((const unsigned*)((const char*)(gbase) + vo_), (PG8_LAS unsigned*)(lds + (bufoff) + ldsw + _i * 8192), 16, 0, 0); } } while (0)
; #define PG8_LDA(dst, b, h) do { _Pragma("unroll") for (int m = 0; m < 4; ++m) _Pragma("unroll") for (int k = 0; k < 2; ++k) dst[m][k] = *(const PG8_LAS bf16x8*)(lds + PG8_SA(b, h) + aoff + m * 2048 + k * 1024); } while (0)
; #define PG8_LDB(dst, b, h) do { _Pragma("unroll") for (int n = 0; n < 2; ++n) _Pragma("unroll") for (int k = 0; k < 2; ++k) dst[n][k] = *(const PG8_LAS bf16x8*)(lds + PG8_SB(b, h) + boff + n * 2048 + k * 1024); } while (0)
; #define PG8_WAIT_V(n) asm volatile("s_waitcnt vmcnt(" #n ")" ::: "memory")
; #define PG8_WAIT_L(n) asm volatile("s_waitcnt lgkmcnt(" #n ")" ::: "memory")
; #define PG8_BAR __builtin_amdgcn_s_barrier()
; #define PG8_SCHED __builtin_amdgcn_sched_barrier(0)
; template <class Epi, class Sched, bool ALIGN_EPI = false, bool SP2 = false, bool FP8 = false>
; __device__ __forceinline__ void gemm_phase(PG8_LAS unsigned char* lds, const Gemm g, const Sched& S, const Epi& E) {
;     ...
;             PG8_WAIT_V(8); PG8_WAIT_L(0); PG8_BAR; PG8_MMA(1, 0, At, B0); PG8_MMA(1, 1, At, B1); PG8_BAR; PG8_SCHED;
;             PG8_LDB(B0, 1, 0); PG8_LDB(B1, 1, 1); PG8_SCHED; PG8_LDA(At, 1, 0); PG8_STAGE(PG8_SA(0, 1), a2 + hstep, voffA);
;             PG8_WAIT_V(8); PG8_WAIT_L(0); PG8_BAR; PG8_MMA(0, 0, At, B0); PG8_MMA(0, 1, At, B1); PG8_BAR; PG8_SCHED;
;             PG8_LDA(At, 1, 1); PG8_STAGE(PG8_SB(1, 0), b3, voffB); PG8_STAGE(PG8_SB(1, 1), b3 + hstep, voffB); PG8_STAGE(PG8_SA(1, 0), a3, voffA);
.Lmy_rd_P6_1:
	s_mov_b32 s99, 0
	s_waitcnt lgkmcnt(0)
	s_barrier
	s_setprio 1
	s_waitcnt lgkmcnt(0)
	v_mfma_f32_16x16x32_bf16 v[60:63], v[128:131], v[178:181], v[60:63]
	v_mfma_f32_16x16x32_bf16 v[56:59], v[136:139], v[178:181], v[56:59]
	v_mfma_f32_16x16x32_bf16 v[44:47], v[128:131], v[186:189], v[44:47]
	v_mfma_f32_16x16x32_bf16 v[40:43], v[136:139], v[186:189], v[40:43]
	v_mfma_f32_16x16x32_bf16 v[28:31], v[128:131], v[194:197], v[28:31]
	v_mfma_f32_16x16x32_bf16 v[24:27], v[136:139], v[194:197], v[24:27]
	v_mfma_f32_16x16x32_bf16 v[12:15], v[128:131], v[210:213], v[12:15]
	v_mfma_f32_16x16x32_bf16 v[8:11], v[136:139], v[210:213], v[8:11]
	v_mfma_f32_16x16x32_bf16 v[60:63], v[132:135], v[182:185], v[60:63]
	v_mfma_f32_16x16x32_bf16 v[56:59], v[140:143], v[182:185], v[56:59]
	v_mfma_f32_16x16x32_bf16 v[44:47], v[132:135], v[190:193], v[44:47]
	v_mfma_f32_16x16x32_bf16 v[40:43], v[140:143], v[190:193], v[40:43]
	v_mfma_f32_16x16x32_bf16 v[28:31], v[132:135], v[206:209], v[28:31]
	v_mfma_f32_16x16x32_bf16 v[24:27], v[140:143], v[206:209], v[24:27]
	v_mfma_f32_16x16x32_bf16 v[12:15], v[132:135], v[214:217], v[12:15]
	v_mfma_f32_16x16x32_bf16 v[8:11], v[140:143], v[214:217], v[8:11]
	s_setprio 0
	s_setprio 1
	v_mfma_f32_16x16x32_bf16 v[52:55], v[144:147], v[178:181], v[52:55]
	v_mfma_f32_16x16x32_bf16 v[48:51], v[170:173], v[178:181], v[48:51]
	v_mfma_f32_16x16x32_bf16 v[36:39], v[144:147], v[186:189], v[36:39]
	v_mfma_f32_16x16x32_bf16 v[32:35], v[170:173], v[186:189], v[32:35]
	v_mfma_f32_16x16x32_bf16 v[20:23], v[144:147], v[194:197], v[20:23]
	v_mfma_f32_16x16x32_bf16 v[16:19], v[170:173], v[194:197], v[16:19]
	v_mfma_f32_16x16x32_bf16 v[4:7], v[144:147], v[210:213], v[4:7]
	v_mfma_f32_16x16x32_bf16 v[0:3], v[170:173], v[210:213], v[0:3]
	v_mfma_f32_16x16x32_bf16 v[52:55], v[148:151], v[182:185], v[52:55]
	v_mfma_f32_16x16x32_bf16 v[48:51], v[174:177], v[182:185], v[48:51]
	v_mfma_f32_16x16x32_bf16 v[36:39], v[148:151], v[190:193], v[36:39]
	v_mfma_f32_16x16x32_bf16 v[32:35], v[174:177], v[190:193], v[32:35]
	v_mfma_f32_16x16x32_bf16 v[20:23], v[148:151], v[206:209], v[20:23]
	v_mfma_f32_16x16x32_bf16 v[16:19], v[174:177], v[206:209], v[16:19]
	v_mfma_f32_16x16x32_bf16 v[4:7], v[148:151], v[214:217], v[4:7]
	v_mfma_f32_16x16x32_bf16 v[0:3], v[174:177], v[214:217], v[0:3]
	s_setprio 0
	s_barrier
	s_add_i32 s64, 0, 0x18000
	s_add_i32 s65, 0, 0x1c000
	v_add_u32_e32 v140, s64, v199
	v_add_u32_e32 v174, s65, v199
	ds_read_b128 v[128:131], v140
	ds_read_b128 v[132:135], v140 offset:1024
	ds_read_b128 v[136:139], v140 offset:2048
	ds_read_b128 v[140:143], v140 offset:3072
	ds_read_b128 v[144:147], v174
	ds_read_b128 v[148:151], v174 offset:1024
	ds_read_b128 v[170:173], v174 offset:2048
	ds_read_b128 v[174:177], v174 offset:3072
	s_add_u32 s44, s44, 0x100000
	s_addc_u32 s45, s45, 0
	s_mov_b32 m0, s49
	v_lshl_add_u64 v[226:227], s[44:45], 0, v[152:153]
	ds_read_b128 v[178:181], v203 offset:32768
	ds_read_b128 v[182:185], v203 offset:33792
	ds_read_b128 v[186:189], v203 offset:34816
	ds_read_b128 v[190:193], v203 offset:35840
	ds_read_b128 v[194:197], v203 offset:36864
	ds_read_b128 v[206:209], v203 offset:37888
	ds_read_b128 v[210:213], v203 offset:38912
	ds_read_b128 v[214:217], v203 offset:39936
	global_load_lds_dwordx4 v[226:227], off
	v_lshl_add_u64 v[226:227], s[44:45], 0, v[156:157]
	s_mov_b32 m0, s50
	s_nop 0
	global_load_lds_dwordx4 v[226:227], off
	s_waitcnt vmcnt(8)
	s_waitcnt lgkmcnt(0)
	s_barrier
	s_setprio 1
	s_waitcnt lgkmcnt(0)
	v_mfma_f32_16x16x32_bf16 v[124:127], v[128:131], v[178:181], v[124:127]
	v_mfma_f32_16x16x32_bf16 v[120:123], v[136:139], v[178:181], v[120:123]
	v_mfma_f32_16x16x32_bf16 v[108:111], v[128:131], v[186:189], v[108:111]
	v_mfma_f32_16x16x32_bf16 v[104:107], v[136:139], v[186:189], v[104:107]
	v_mfma_f32_16x16x32_bf16 v[92:95], v[128:131], v[194:197], v[92:95]
	v_mfma_f32_16x16x32_bf16 v[88:91], v[136:139], v[194:197], v[88:91]
	v_mfma_f32_16x16x32_bf16 v[76:79], v[128:131], v[210:213], v[76:79]
	v_mfma_f32_16x16x32_bf16 v[72:75], v[136:139], v[210:213], v[72:75]
	v_mfma_f32_16x16x32_bf16 v[124:127], v[132:135], v[182:185], v[124:127]
	v_mfma_f32_16x16x32_bf16 v[120:123], v[140:143], v[182:185], v[120:123]
	v_mfma_f32_16x16x32_bf16 v[108:111], v[132:135], v[190:193], v[108:111]
	v_mfma_f32_16x16x32_bf16 v[104:107], v[140:143], v[190:193], v[104:107]
	v_mfma_f32_16x16x32_bf16 v[92:95], v[132:135], v[206:209], v[92:95]
	v_mfma_f32_16x16x32_bf16 v[88:91], v[140:143], v[206:209], v[88:91]
	v_mfma_f32_16x16x32_bf16 v[76:79], v[132:135], v[214:217], v[76:79]
	v_mfma_f32_16x16x32_bf16 v[72:75], v[140:143], v[214:217], v[72:75]
	s_setprio 0
	s_setprio 1
	v_mfma_f32_16x16x32_bf16 v[116:119], v[144:147], v[178:181], v[116:119]
	v_mfma_f32_16x16x32_bf16 v[112:115], v[170:173], v[178:181], v[112:115]
	v_mfma_f32_16x16x32_bf16 v[100:103], v[144:147], v[186:189], v[100:103]
	v_mfma_f32_16x16x32_bf16 v[96:99], v[170:173], v[186:189], v[96:99]
	v_mfma_f32_16x16x32_bf16 v[84:87], v[144:147], v[194:197], v[84:87]
	v_mfma_f32_16x16x32_bf16 v[80:83], v[170:173], v[194:197], v[80:83]
	v_mfma_f32_16x16x32_bf16 v[68:71], v[144:147], v[210:213], v[68:71]
	v_mfma_f32_16x16x32_bf16 v[64:67], v[170:173], v[210:213], v[64:67]
	v_mfma_f32_16x16x32_bf16 v[116:119], v[148:151], v[182:185], v[116:119]
	v_mfma_f32_16x16x32_bf16 v[112:115], v[174:177], v[182:185], v[112:115]
	v_mfma_f32_16x16x32_bf16 v[100:103], v[148:151], v[190:193], v[100:103]
	v_mfma_f32_16x16x32_bf16 v[96:99], v[174:177], v[190:193], v[96:99]
	v_mfma_f32_16x16x32_bf16 v[84:87], v[148:151], v[206:209], v[84:87]
	v_mfma_f32_16x16x32_bf16 v[80:83], v[174:177], v[206:209], v[80:83]
	v_mfma_f32_16x16x32_bf16 v[68:71], v[148:151], v[214:217], v[68:71]
	v_mfma_f32_16x16x32_bf16 v[64:67], v[174:177], v[214:217], v[64:67]
	s_setprio 0
	s_barrier
; #define PG8_STAGE(bufoff, gbase, voff) do { _Pragma("unroll") for (int _i = 0; _i < 2; ++_i) { unsigned vo_ = (voff)[_i]; if constexpr (FP8) asm volatile("" : "+v"(vo_)); \
;         __builtin_amdgcn_global_load_lds((const unsigned*)((const char*)(gbase) + vo_), (PG8_LAS unsigned*)(lds + (bufoff) + ldsw + _i * 8192), 16, 0, 0); } } while (0)
; #define PG8_LDA(dst, b, h) do { _Pragma("unroll") for (int m = 0; m < 4; ++m) _Pragma("unroll") for (int k = 0; k < 2; ++k) dst[m][k] = *(const PG8_LAS bf16x8*)(lds + PG8_SA(b, h) + aoff + m * 2048 + k * 1024); } while (0)
; #define PG8_WAIT_V(n) asm volatile("s_waitcnt vmcnt(" #n ")" ::: "memory")
; #define PG8_WAIT_L(n) asm volatile("s_waitcnt lgkmcnt(" #n ")" ::: "memory")
; #define PG8_BAR __builtin_amdgcn_s_barrier()
; #define PG8_SCHED __builtin_amdgcn_sched_barrier(0)
; template <class Epi, class Sched, bool ALIGN_EPI = false, bool SP2 = false, bool FP8 = false>
; __device__ __forceinline__ void gemm_phase(PG8_LAS unsigned char* lds, const Gemm g, const Sched& S, const Epi& E) {
;     ...
;             PG8_LDA(At, 1, 1); PG8_STAGE(PG8_SB(1, 0), b3, voffB); PG8_STAGE(PG8_SB(1, 1), b3 + hstep, voffB); PG8_STAGE(PG8_SA(1, 0), a3, voffA);
;             PG8_WAIT_V(8); PG8_WAIT_L(0); PG8_BAR; PG8_MMA(1, 0, At, B0); PG8_MMA(1, 1, At, B1); PG8_BAR; PG8_SCHED;
	s_add_i32 s44, s64, s46
	v_lshl_add_u64 v[218:219], v[218:219], 0, s[12:13]
	s_mov_b32 m0, s44
	ds_read_b128 v[178:181], v203 offset:49152
	ds_read_b128 v[182:185], v203 offset:50176
	ds_read_b128 v[186:189], v203 offset:51200
	ds_read_b128 v[190:193], v203 offset:52224
	ds_read_b128 v[194:197], v203 offset:53248
	ds_read_b128 v[206:209], v203 offset:54272
	ds_read_b128 v[210:213], v203 offset:55296
	ds_read_b128 v[214:217], v203 offset:56320
	global_load_lds_dwordx4 v[218:219], off
	s_add_i32 m0, s44, 0x2000
	s_add_u32 s42, s42, 0x100080
	v_lshl_add_u64 v[218:219], v[220:221], 0, s[12:13]
	s_addc_u32 s43, s43, 0
	s_add_i32 s44, s65, s46
	global_load_lds_dwordx4 v[218:219], off
	v_lshl_add_u64 v[218:219], s[42:43], 0, v[154:155]
	s_mov_b32 m0, s44
	s_nop 0
	global_load_lds_dwordx4 v[218:219], off
	v_lshl_add_u64 v[218:219], s[42:43], 0, v[158:159]
	s_add_i32 m0, s44, 0x2000
	s_nop 0
	global_load_lds_dwordx4 v[218:219], off
	v_lshl_add_u64 v[218:219], v[222:223], 0, s[12:13]
	s_mov_b32 m0, s54
	s_nop 0
	global_load_lds_dwordx4 v[218:219], off
	v_lshl_add_u64 v[218:219], v[224:225], 0, s[12:13]
	s_mov_b32 m0, s55
	s_nop 0
	global_load_lds_dwordx4 v[218:219], off
	s_waitcnt vmcnt(8)
	s_waitcnt lgkmcnt(0)
	s_barrier
	s_setprio 1
	s_waitcnt lgkmcnt(0)
	v_mfma_f32_16x16x32_bf16 v[60:63], v[128:131], v[178:181], v[60:63]
	v_mfma_f32_16x16x32_bf16 v[56:59], v[136:139], v[178:181], v[56:59]
	v_mfma_f32_16x16x32_bf16 v[44:47], v[128:131], v[186:189], v[44:47]
	v_mfma_f32_16x16x32_bf16 v[40:43], v[136:139], v[186:189], v[40:43]
	v_mfma_f32_16x16x32_bf16 v[28:31], v[128:131], v[194:197], v[28:31]
	v_mfma_f32_16x16x32_bf16 v[24:27], v[136:139], v[194:197], v[24:27]
	v_mfma_f32_16x16x32_bf16 v[12:15], v[128:131], v[210:213], v[12:15]
	v_mfma_f32_16x16x32_bf16 v[8:11], v[136:139], v[210:213], v[8:11]
	v_mfma_f32_16x16x32_bf16 v[60:63], v[132:135], v[182:185], v[60:63]
	v_mfma_f32_16x16x32_bf16 v[56:59], v[140:143], v[182:185], v[56:59]
	v_mfma_f32_16x16x32_bf16 v[44:47], v[132:135], v[190:193], v[44:47]
	v_mfma_f32_16x16x32_bf16 v[40:43], v[140:143], v[190:193], v[40:43]
	v_mfma_f32_16x16x32_bf16 v[28:31], v[132:135], v[206:209], v[28:31]
	v_mfma_f32_16x16x32_bf16 v[24:27], v[140:143], v[206:209], v[24:27]
	v_mfma_f32_16x16x32_bf16 v[12:15], v[132:135], v[214:217], v[12:15]
	v_mfma_f32_16x16x32_bf16 v[8:11], v[140:143], v[214:217], v[8:11]
	s_setprio 0
	s_setprio 1
	v_mfma_f32_16x16x32_bf16 v[52:55], v[144:147], v[178:181], v[52:55]
	v_mfma_f32_16x16x32_bf16 v[48:51], v[170:173], v[178:181], v[48:51]
	v_mfma_f32_16x16x32_bf16 v[36:39], v[144:147], v[186:189], v[36:39]
	v_mfma_f32_16x16x32_bf16 v[32:35], v[170:173], v[186:189], v[32:35]
	v_mfma_f32_16x16x32_bf16 v[20:23], v[144:147], v[194:197], v[20:23]
	v_mfma_f32_16x16x32_bf16 v[16:19], v[170:173], v[194:197], v[16:19]
	v_mfma_f32_16x16x32_bf16 v[4:7], v[144:147], v[210:213], v[4:7]
	v_mfma_f32_16x16x32_bf16 v[0:3], v[170:173], v[210:213], v[0:3]
	v_mfma_f32_16x16x32_bf16 v[52:55], v[148:151], v[182:185], v[52:55]
	v_mfma_f32_16x16x32_bf16 v[48:51], v[174:177], v[182:185], v[48:51]
	v_mfma_f32_16x16x32_bf16 v[36:39], v[148:151], v[190:193], v[36:39]
	v_mfma_f32_16x16x32_bf16 v[32:35], v[174:177], v[190:193], v[32:35]
	v_mfma_f32_16x16x32_bf16 v[20:23], v[148:151], v[206:209], v[20:23]
	v_mfma_f32_16x16x32_bf16 v[16:19], v[174:177], v[206:209], v[16:19]
	v_mfma_f32_16x16x32_bf16 v[4:7], v[148:151], v[214:217], v[4:7]
	v_mfma_f32_16x16x32_bf16 v[0:3], v[174:177], v[214:217], v[0:3]
	s_setprio 0
	s_barrier
	s_add_i32 s63, s63, 2
	s_add_u32 s40, s40, 0x100
	s_addc_u32 s41, s41, 0
	s_add_u32 s61, s61, 0x100
	s_addc_u32 s62, s62, 0
	s_cmp_gt_u32 s63, 61
	s_cbranch_scc0 .LBB0_427
	s_and_b64 vcc, exec, s[14:15]
	s_cbranch_vccz .LBB0_430
